# MLA loop: no P lane swaps (V^T reads in accumulator key order), K/V global loads of the next tile issued right after the LDS stores of the staging step instead of at the top of the next half
# speedup vs baseline: 1.0524x; 1.0023x over previous
; #define LAS __attribute__((address_space(3)))
; template <int DQK, int SDEPTH, bool OUT_BF16, int QREG = DQK / 16, bool OUT_F16 = false> ...
;     ...
;   LAS char* Qp = lds + 2 * SHM_V + 2 * SHM_K + NW * 64 * 4 + wid * (QLDS * 1024) + lane * 16;
;   float m_reg = -1e30f, l_reg = 0; f32x16 o[4] = {}; bf16x8 qr[QREG];
;   const bf16_t* Qw = Qb + (long)(wid * QBLK + r32) * DQK + hi * 8;
; #pragma unroll
;   for (int d0 = 0; d0 < QREG; ++d0) qr[d0] = *reinterpret_cast<const bf16x8*>(Qw + d0 * 16);
;   if constexpr (QLDS > 0) {
;     static_assert(DQK != 192 || QLDS >= 4, "rope fragments must be among the LDS ones");
; #pragma unroll
;     for (int d0 = QREG; d0 < (DQK == 192 ? 8 : DQK / 16); ++d0) *(LAS bf16x8*)(Qp + (d0 - QREG) * 1024) = *reinterpret_cast<const bf16x8*>(Qw + d0 * 16);
;     if constexpr (DQK == 192) {
;       u32x4 f[4];
; #pragma unroll
;       for (int d0 = 0; d0 < 4; ++d0) f[d0] = *reinterpret_cast<const u32x4*>(Qw + (8 + d0) * 16);
;       if (tq0 >= 0) { const int t = tq0 + wid * QBLK + r32; const f32x2* rr = rt + (t >> 6) * 16 + 8 * hi; const f32x2* rc = rt + (t & 63) * 16 + 8 * hi;
; #pragma unroll
;         for (int w2 = 0; w2 < 4; ++w2) { float a0 = bflo(f[0][w2]), a1 = bfhi(f[0][w2]), b0 = bflo(f[1][w2]), b1 = bfhi(f[1][w2]), c0 = bflo(f[2][w2]), c1 = bfhi(f[2][w2]), e0 = bflo(f[3][w2]), e1 = bfhi(f[3][w2]);
;           const f32x2 r0 = rr[2 * w2], r1 = rr[2 * w2 + 1], s0 = rc[2 * w2], s1 = rc[2 * w2 + 1];
;           f[0][w2] = cvtpk(a0 * r0.x - b0 * r0.y, a1 * r1.x - b1 * r1.y); f[1][w2] = cvtpk(a0 * r0.y + b0 * r0.x, a1 * r1.y + b1 * r1.x);
;           f[2][w2] = cvtpk(c0 * s0.x - e0 * s0.y, c1 * s1.x - e1 * s1.y); f[3][w2] = cvtpk(c0 * s0.y + e0 * s0.x, c1 * s1.y + e1 * s1.x); } }
; #pragma unroll
;       for (int d0 = 0; d0 < 4; ++d0) *(LAS u32x4*)(Qp + (8 - QREG + d0) * 1024) = f[d0];
;     }
;   }
;     ...
;   const int sr = tid >> 4, sc = (tid & 15) * 8, vst0 = v_st(sr, sc), vst1 = v_st(32 + sr, sc);
;   int krow[NKC], kcol[NKC];
; #pragma unroll
;   for (int i = 0; i < NKC; ++i) { const int ci = tid + i * 512; krow[i] = ci / CPR; kcol[i] = (ci % CPR) * 8; }
;   const int vb0 = (int)(uintptr_t)V_lds + v_rd_base(lane);
;   struct { bf16x8 vs0, vs1, ks[NKC]; } sr_[SDEPTH];
;     ...
;   f32x16 pA0, pA1, pB0, pB1; float mnA, mnB, alA, alB; bf16x8 pa0, pa1, pa2, pa3; const int NT = seq / KVBLK;
;   constexpr int SE = 0, SO = SDEPTH - 1;
.LBB0_747:
	s_waitcnt vmcnt(3)
	ds_write_b128 v162, v[2:5] offset:4096
	s_waitcnt vmcnt(2)
	ds_write_b128 v162, v[6:9] offset:5120
	s_waitcnt vmcnt(1)
	ds_write_b128 v162, v[10:13] offset:6144
	s_waitcnt vmcnt(0)
	ds_write_b128 v162, v[14:17] offset:7168
	v_ashrrev_i32_e32 v2, 4, v34
	v_and_b32_e32 v5, 0xfffff0, v2
	v_lshlrev_b32_e32 v6, 1, v2
	v_lshlrev_b32_e32 v3, 3, v84
	v_and_or_b32 v5, v6, 8, v5
	v_and_b32_e32 v4, 0x78, v3
	v_lshrrev_b32_e32 v5, 1, v5
	v_bfe_u32 v3, v3, 5, 2
	v_or_b32_e32 v5, v5, v3
	v_lshrrev_b32_e32 v6, 1, v2
	v_lshlrev_b32_e32 v22, 9, v5
	v_and_b32_e32 v5, 3, v2
	v_and_or_b32 v5, v6, 4, v5
	v_add_u32_e32 v6, 32, v2
	v_and_b32_e32 v7, 0xfffff0, v6
	v_lshlrev_b32_e32 v8, 1, v6
	v_and_or_b32 v7, v8, 8, v7
	v_lshrrev_b32_e32 v7, 1, v7
	v_or_b32_e32 v3, v7, v3
	v_mul_hi_i32 v7, v34, s31
	v_lshrrev_b32_e32 v8, 31, v7
	v_ashrrev_i32_e32 v7, 2, v7
	v_add_u32_e32 v58, v7, v8
	v_mul_lo_u32 v7, v58, 24
	v_sub_u32_e32 v24, v34, v7
	v_add_u32_e32 v7, 0x200, v34
	v_mul_hi_i32 v8, v7, s31
	v_lshrrev_b32_e32 v9, 31, v8
	v_ashrrev_i32_e32 v8, 2, v8
	v_add_u32_e32 v62, v8, v9
	v_mul_lo_u32 v8, v62, 24
	v_sub_u32_e32 v25, v7, v8
	v_add_u32_e32 v7, 0x400, v34
	v_mul_hi_i32 v8, v7, s31
	v_lshrrev_b32_e32 v9, 31, v8
	v_ashrrev_i32_e32 v8, 2, v8
	v_lshlrev_b32_e32 v23, 6, v5
	v_lshlrev_b32_e32 v5, 4, v84
	v_add_u32_e32 v68, v8, v9
	s_mul_i32 s1, s38, 0x210000
	v_lshlrev_b32_e32 v3, 9, v3
	v_mul_lo_u32 v8, v68, 24
	v_and_b32_e32 v27, 48, v5
	s_mul_hi_i32 s0, s38, 0x210000
	s_add_u32 s1, s4, s1
	v_sub_u32_e32 v26, v7, v8
	v_or3_b32 v28, v3, v23, v27
	v_lshlrev_b32_e32 v3, 3, v85
	v_and_b32_e32 v5, 0xc0, v35
	v_lshlrev_b32_e32 v7, 1, v85
	s_addc_u32 s0, s5, s0
	v_and_or_b32 v5, v3, 24, v5
	v_and_b32_e32 v7, 32, v7
	v_and_b32_e32 v3, 0x100, v3
	s_add_u32 s2, s1, 0x44874000
	v_or3_b32 v86, v5, v7, v3
	v_ashrrev_i32_e32 v3, 31, v2
	s_addc_u32 s3, s0, 0
	v_lshlrev_b64 v[70:71], 8, v[2:3]
	v_lshl_add_u64 v[2:3], s[2:3], 0, v[70:71]
	v_lshlrev_b32_e32 v8, 1, v4
	v_mov_b32_e32 v9, v1
	v_lshl_add_u64 v[54:55], v[2:3], 0, v[8:9]
	s_mul_i32 s1, s38, 0x318000
	global_load_dwordx4 v[2:5], v[54:55], off
	s_mul_hi_i32 s0, s38, 0x318000
	s_add_u32 s1, s4, s1
	s_addc_u32 s8, s5, s0
	s_add_u32 s0, s1, 0x42fb4000
	s_addc_u32 s1, s8, 0
	v_and_b32_e32 v18, 0x3fffffc0, v34
	s_add_i32 s8, 0, 0x14000
	v_lshl_add_u32 v143, v18, 2, s8
	v_lshlrev_b32_e32 v10, 3, v24
	v_lshlrev_b32_e32 v14, 3, v25
	v_lshlrev_b32_e32 v18, 3, v26
	v_ashrrev_i32_e32 v7, 31, v6
	v_lshlrev_b64 v[6:7], 8, v[6:7]
	v_ashrrev_i32_e32 v11, 31, v10
	v_mov_b64_e32 v[66:67], s[0:1]
	v_ashrrev_i32_e32 v15, 31, v14
	v_ashrrev_i32_e32 v19, 31, v18
	v_lshl_add_u64 v[6:7], s[2:3], 0, v[6:7]
	v_mad_i64_i32 v[12:13], s[0:1], v58, s27, v[66:67]
	v_lshlrev_b64 v[74:75], 1, v[10:11]
	v_mad_i64_i32 v[16:17], s[0:1], v62, s27, v[66:67]
	v_lshlrev_b64 v[78:79], 1, v[14:15]
	v_mad_i64_i32 v[20:21], s[0:1], v68, s27, v[66:67]
	v_lshlrev_b64 v[82:83], 1, v[18:19]
	v_lshl_add_u64 v[6:7], v[6:7], 0, v[8:9]
	v_lshl_add_u64 v[10:11], v[12:13], 0, v[74:75]
	v_lshl_add_u64 v[14:15], v[16:17], 0, v[78:79]
	v_lshl_add_u64 v[18:19], v[20:21], 0, v[82:83]
	global_load_dwordx4 v[6:9], v[6:7], off
	v_or3_b32 v22, v22, v23, v27
	global_load_dwordx4 v[10:13], v[10:11], off
	v_add_u32_e32 v167, 0, v22
	global_load_dwordx4 v[14:17], v[14:15], off
	v_mad_i64_i32 v[72:73], s[2:3], v58, s27, 0
	global_load_dwordx4 v[18:21], v[18:19], off
	s_waitcnt vmcnt(0)
	v_mad_i64_i32 v[76:77], s[0:1], v62, s27, 0
	v_mad_i64_i32 v[80:81], s[0:1], v68, s27, 0
	v_mad_u32_u24 v57, v160, s27, 0
	v_add_u32_e32 v168, 0, v28
	v_or_b32_e32 v50, 32, v0
	s_movk_i32 s0, 0x4000
	s_mov_b32 s8, s9
	s_mov_b32 s10, s9
	s_mov_b32 s11, s9
	s_mov_b32 s12, s9
	s_mov_b32 s13, s9
	s_mov_b32 s14, s9
	s_mov_b32 s15, s9
	s_mov_b32 s16, s9
	s_mov_b32 s17, s9
	s_mov_b32 s18, s9
	s_mov_b32 s19, s9
	s_mov_b32 s20, s9
	s_mov_b32 s21, s9
	s_mov_b32 s22, s9
	s_mov_b32 s23, s9
	s_mov_b32 s41, 2
	v_add_u32_e32 v163, 0, v86
	v_lshl_add_u32 v164, v160, 2, v143
	v_mov_b32_e32 v166, 0
	s_waitcnt vmcnt(4)
	ds_write_b128 v167, v[2:5]
	v_bitop3_b32 v2, v58, v24, 7 bitop3:0x6c
	v_lshl_add_u32 v2, v2, 4, 0
	v_add_u32_e32 v169, v2, v72
	v_bitop3_b32 v2, v62, v25, 7 bitop3:0x6c
	v_lshl_add_u32 v2, v2, 4, 0
	v_add_u32_e32 v170, v2, v76
	v_bitop3_b32 v2, v68, v26, 7 bitop3:0x6c
	v_lshl_add_u32 v2, v2, 4, 0
	v_add_u32_e32 v171, v2, v80
	v_lshlrev_b32_e32 v2, 4, v160
	v_and_b32_e32 v56, 0x70, v2
	v_xad_u32 v172, v0, v56, v57
	v_xad_u32 v173, v50, v56, v57
	v_add_u32_e32 v58, 64, v58
	v_add_u32_e32 v62, 64, v62
	v_add_u32_e32 v68, 64, v68
	v_add_u32_e32 v196, 0xe000, v172
	v_add_u32_e32 v195, 0xe000, v173
	s_waitcnt vmcnt(3)
	ds_write_b128 v168, v[6:9]
	s_waitcnt vmcnt(2)
	ds_write_b128 v169, v[10:13] offset:32768
	s_waitcnt vmcnt(1)
	ds_write_b128 v170, v[14:17] offset:32768
	v_mov_b64_e32 v[2:3], s[8:9]
	v_mov_b64_e32 v[16:17], s[22:23]
	s_waitcnt vmcnt(0)
	ds_write_b128 v171, v[18:21] offset:32768
	s_waitcnt lgkmcnt(0)
	s_barrier
; DI int v_st(int k, int c) { const int kk = (k & ~0xC) | ((k & 4) << 1) | ((k & 8) >> 1); return ((kk >> 3) * 4 + (c >> 5)) * 512 + ((kk & 7) * 32 + (c & 31)) * 2; }
; DI int v_rd_base(int lane) { return ((lane & 3) << 3) | (((lane >> 2) & 3) << 6) | (((lane >> 4) & 1) << 5) | (((lane >> 5) & 1) << 8); }
; #define SLOAD(i, k0) do { sr_[i].vs0 = *reinterpret_cast<const bf16x8*>(&Vh[(long)((k0) + sr) * DV + sc]); sr_[i].vs1 = *reinterpret_cast<const bf16x8*>(&Vh[(long)((k0) + 32 + sr) * DV + sc]); \
;     _Pragma("unroll") for (int _c = 0; _c < NKC; ++_c) sr_[i].ks[_c] = *reinterpret_cast<const bf16x8*>(&Kh[(long)((k0) + krow[_c]) * DQK + kcol[_c]]); } while (0)
; #define SWRITE(b, i) do { *(LAS bf16x8*)(V_lds + (b) * SHM_V + vst0) = sr_[i].vs0; *(LAS bf16x8*)(V_lds + (b) * SHM_V + vst1) = sr_[i].vs1; \
;     _Pragma("unroll") for (int _c = 0; _c < NKC; ++_c) *(LAS bf16x8*)(K_lds + (b) * SHM_K + kswz<DQK>(krow[_c], kcol[_c] * 2)) = sr_[i].ks[_c]; } while (0)
; #define SWAIT() do { if constexpr (SDEPTH == 2) { if constexpr (NKC == 1) asm volatile("s_waitcnt vmcnt(3)" ::: "memory"); else if constexpr (NKC == 2) asm volatile("s_waitcnt vmcnt(4)" ::: "memory"); else asm volatile("s_waitcnt vmcnt(5)" ::: "memory"); } \
;     else asm volatile("s_waitcnt vmcnt(0)" ::: "memory"); } while (0)
; template <int DQK, int SDEPTH, bool OUT_BF16, int QREG = DQK / 16, bool OUT_F16 = false> ...
;     ...
;   const int sr = tid >> 4, sc = (tid & 15) * 8, vst0 = v_st(sr, sc), vst1 = v_st(32 + sr, sc);
;   int krow[NKC], kcol[NKC];
; #pragma unroll
;   for (int i = 0; i < NKC; ++i) { const int ci = tid + i * 512; krow[i] = ci / CPR; kcol[i] = (ci % CPR) * 8; }
;   const int vb0 = (int)(uintptr_t)V_lds + v_rd_base(lane);
;   struct { bf16x8 vs0, vs1, ks[NKC]; } sr_[SDEPTH];
;     ...
;   f32x16 pA0, pA1, pB0, pB1; float mnA, mnB, alA, alB; bf16x8 pa0, pa1, pa2, pa3; const int NT = seq / KVBLK;
;   constexpr int SE = 0, SO = SDEPTH - 1;
;   SLOAD(SE, 0); asm volatile("s_waitcnt vmcnt(0)" ::: "memory"); SWRITE(0, SE); __syncthreads();
;   QKT(pA0, pA1, K_lds); partialSM(pA0, pA1, m_reg, mnA, alA, SCALE);
;   SLOAD(SO, KVBLK); if constexpr (SDEPTH == 2) { if (2 < NT) SLOAD(SE, 2 * KVBLK); }
;   SWAIT(); SWRITE(1, SO); __syncthreads();
	ds_read_b128 v[18:21], v172 offset:32768
	ds_read_b128 v[22:25], v172 offset:45056
	s_waitcnt lgkmcnt(1)
	v_mfma_f32_32x32x16_bf16 v[34:49], v[18:21], v[110:113], 0
	ds_read_b128 v[50:53], v173 offset:32768
	ds_read_b128 v[88:91], v173 offset:45056
	v_mov_b64_e32 v[4:5], s[10:11]
	v_mov_b64_e32 v[6:7], s[12:13]
	v_mov_b64_e32 v[8:9], s[14:15]
	v_mov_b64_e32 v[10:11], s[16:17]
	v_mov_b64_e32 v[12:13], s[18:19]
	v_mov_b64_e32 v[14:15], s[20:21]
	s_waitcnt lgkmcnt(2)
	v_mfma_f32_32x32x16_bf16 v[18:33], v[22:25], v[110:113], 0
	s_waitcnt lgkmcnt(1)
	v_mfma_f32_32x32x16_bf16 v[34:49], v[50:53], v[106:109], v[34:49]
	v_or_b32_e32 v50, 64, v0
	v_xad_u32 v174, v50, v56, v57
	v_add_u32_e32 v193, 0xe000, v174
	s_waitcnt lgkmcnt(0)
	v_mfma_f32_32x32x16_bf16 v[18:33], v[88:91], v[106:109], v[18:33]
	ds_read_b128 v[50:53], v174 offset:32768
	ds_read_b128 v[88:91], v174 offset:45056
	s_waitcnt lgkmcnt(1)
	v_mfma_f32_32x32x16_bf16 v[34:49], v[50:53], v[102:105], v[34:49]
	v_or_b32_e32 v50, 0x60, v0
	v_xad_u32 v175, v50, v56, v57
	v_add_u32_e32 v192, 0xe000, v175
	s_waitcnt lgkmcnt(0)
	v_mfma_f32_32x32x16_bf16 v[18:33], v[88:91], v[102:105], v[18:33]
	ds_read_b128 v[50:53], v175 offset:32768
	ds_read_b128 v[88:91], v175 offset:45056
	s_waitcnt lgkmcnt(1)
	v_mfma_f32_32x32x16_bf16 v[34:49], v[50:53], v[98:101], v[34:49]
	v_or_b32_e32 v50, 0x80, v0
	v_xad_u32 v176, v50, v56, v57
	v_add_u32_e32 v191, 0xe000, v176
	s_waitcnt lgkmcnt(0)
	v_mfma_f32_32x32x16_bf16 v[18:33], v[88:91], v[98:101], v[18:33]
	ds_read_b128 v[50:53], v176 offset:32768
	ds_read_b128 v[88:91], v176 offset:45056
	ds_read_b128 v[92:95], v162
	s_waitcnt lgkmcnt(0)
	v_mfma_f32_32x32x16_bf16 v[34:49], v[50:53], v[92:95], v[34:49]
	v_or_b32_e32 v50, 0xa0, v0
	v_xad_u32 v177, v50, v56, v57
	v_add_u32_e32 v190, 0xe000, v177
	v_mfma_f32_32x32x16_bf16 v[18:33], v[88:91], v[92:95], v[18:33]
	ds_read_b128 v[50:53], v177 offset:32768
	ds_read_b128 v[88:91], v177 offset:45056
	ds_read_b128 v[92:95], v162 offset:1024
	s_waitcnt lgkmcnt(0)
	v_mfma_f32_32x32x16_bf16 v[34:49], v[50:53], v[92:95], v[34:49]
	v_or_b32_e32 v50, 0xc0, v0
	v_xad_u32 v178, v50, v56, v57
	v_add_u32_e32 v189, 0xe000, v178
	v_mfma_f32_32x32x16_bf16 v[18:33], v[88:91], v[92:95], v[18:33]
	ds_read_b128 v[50:53], v178 offset:32768
	ds_read_b128 v[88:91], v178 offset:45056
	ds_read_b128 v[92:95], v162 offset:2048
	s_waitcnt lgkmcnt(0)
	v_mfma_f32_32x32x16_bf16 v[34:49], v[50:53], v[92:95], v[34:49]
	v_or_b32_e32 v50, 0xe0, v0
	v_xad_u32 v179, v50, v56, v57
	v_add_u32_e32 v188, 0xe000, v179
	v_mfma_f32_32x32x16_bf16 v[18:33], v[88:91], v[92:95], v[18:33]
	ds_read_b128 v[50:53], v179 offset:32768
	ds_read_b128 v[88:91], v179 offset:45056
	ds_read_b128 v[92:95], v162 offset:3072
	s_waitcnt lgkmcnt(0)
	v_mfma_f32_32x32x16_bf16 v[34:49], v[50:53], v[92:95], v[34:49]
	v_or_b32_e32 v50, 0x100, v0
	v_xad_u32 v180, v50, v56, v57
	v_add_u32_e32 v187, 0xe000, v180
	v_mfma_f32_32x32x16_bf16 v[18:33], v[88:91], v[92:95], v[18:33]
	ds_read_b128 v[50:53], v180 offset:32768
	ds_read_b128 v[88:91], v180 offset:45056
	ds_read_b128 v[92:95], v162 offset:4096
	s_waitcnt lgkmcnt(0)
	v_mfma_f32_32x32x16_bf16 v[34:49], v[50:53], v[92:95], v[34:49]
	v_or_b32_e32 v50, 0x120, v0
	v_xad_u32 v181, v50, v56, v57
	v_add_u32_e32 v186, 0xe000, v181
	v_mfma_f32_32x32x16_bf16 v[18:33], v[88:91], v[92:95], v[18:33]
	ds_read_b128 v[50:53], v181 offset:32768
	ds_read_b128 v[88:91], v181 offset:45056
	ds_read_b128 v[92:95], v162 offset:5120
	s_waitcnt lgkmcnt(0)
	v_mfma_f32_32x32x16_bf16 v[34:49], v[50:53], v[92:95], v[34:49]
	v_or_b32_e32 v50, 0x140, v0
	v_xad_u32 v182, v50, v56, v57
	v_add_u32_e32 v185, 0xe000, v182
	v_mfma_f32_32x32x16_bf16 v[18:33], v[88:91], v[92:95], v[18:33]
	ds_read_b128 v[50:53], v182 offset:32768
	ds_read_b128 v[88:91], v182 offset:45056
	ds_read_b128 v[92:95], v162 offset:6144
	s_waitcnt lgkmcnt(0)
	v_mfma_f32_32x32x16_bf16 v[34:49], v[50:53], v[92:95], v[34:49]
	v_or_b32_e32 v50, 0x160, v0
	v_xad_u32 v183, v50, v56, v57
	v_add_u32_e32 v184, 0xe000, v183
	v_mfma_f32_32x32x16_bf16 v[18:33], v[88:91], v[92:95], v[18:33]
	ds_read_b128 v[50:53], v183 offset:32768
	ds_read_b128 v[88:91], v183 offset:45056
	ds_read_b128 v[92:95], v162 offset:7168
	s_waitcnt lgkmcnt(0)
	v_mfma_f32_32x32x16_bf16 v[34:49], v[50:53], v[92:95], v[34:49]
	v_mfma_f32_32x32x16_bf16 v[18:33], v[88:91], v[92:95], v[18:33]
	s_nop 10
	v_max_f32_e32 v50, v35, v35
	v_max_f32_e32 v51, v34, v34
	v_max_f32_e32 v50, v51, v50
	v_max3_f32 v50, v50, v36, v37
	v_max3_f32 v50, v50, v38, v39
	v_max3_f32 v50, v50, v40, v41
	v_max3_f32 v50, v50, v42, v43
	v_max3_f32 v50, v50, v44, v45
	v_max3_f32 v50, v50, v46, v47
	v_max3_f32 v50, v50, v48, v49
	v_max3_f32 v50, v50, v18, v19
	v_max3_f32 v50, v50, v20, v21
	v_max3_f32 v50, v50, v22, v23
	v_max3_f32 v50, v50, v24, v25
	v_max3_f32 v50, v50, v26, v27
	v_max3_f32 v50, v50, v28, v29
	v_max3_f32 v50, v50, v30, v31
	v_max3_f32 v50, v50, v32, v33
	v_mov_b32_e32 v51, v50
	s_nop 1
	v_permlane32_swap_b32_e32 v50, v51
	v_max_f32_e32 v51, v51, v51
	v_max_f32_e32 v50, v50, v50
	v_max_f32_e32 v87, v50, v51
	v_add_f32_e32 v50, 0x7149f2ca, v87
	v_cmp_ge_f32_e32 vcc, 0x4138aa3b, v50
	v_add_co_u32_e64 v50, s[0:1], s0, v54
	s_cmp_eq_u64 vcc, exec
	s_nop 0
	v_addc_co_u32_e64 v51, s[0:1], 0, v55, s[0:1]
	s_movk_i32 s0, 0x6000
	s_nop 0
	v_add_co_u32_e64 v54, s[0:1], s0, v54
	global_load_dwordx4 v[50:53], v[50:51], off
	s_nop 0
	v_addc_co_u32_e64 v55, s[0:1], 0, v55, s[0:1]
	v_mad_i64_i32 v[58:59], s[0:1], v58, s27, v[66:67]
	global_load_dwordx4 v[54:57], v[54:55], off
	v_lshl_add_u64 v[58:59], v[58:59], 0, v[74:75]
	v_mad_i64_i32 v[62:63], s[0:1], v62, s27, v[66:67]
	global_load_dwordx4 v[58:61], v[58:59], off
	v_lshl_add_u64 v[62:63], v[62:63], 0, v[78:79]
	v_mad_i64_i32 v[66:67], s[0:1], v68, s27, v[66:67]
	global_load_dwordx4 v[62:65], v[62:63], off
	v_lshl_add_u64 v[66:67], v[66:67], 0, v[82:83]
	global_load_dwordx4 v[66:69], v[66:67], off
	s_waitcnt vmcnt(0)
; #define SLOAD(i, k0) do { sr_[i].vs0 = *reinterpret_cast<const bf16x8*>(&Vh[(long)((k0) + sr) * DV + sc]); sr_[i].vs1 = *reinterpret_cast<const bf16x8*>(&Vh[(long)((k0) + 32 + sr) * DV + sc]); \
;     _Pragma("unroll") for (int _c = 0; _c < NKC; ++_c) sr_[i].ks[_c] = *reinterpret_cast<const bf16x8*>(&Kh[(long)((k0) + krow[_c]) * DQK + kcol[_c]]); } while (0)
; DI void partialSM(f32x16& p0, f32x16& p1, float& m_reg, float& mn, float& alpha, const float SCALE) {
;   const float C = SCALE * 1.4426950408889634f;
;   float pmax = p0[0];
; #pragma unroll
;   for (int r = 1; r < 16; ++r) pmax = fmaxf(pmax, p0[r]);
; #pragma unroll
;   for (int r = 0; r < 16; ++r) pmax = fmaxf(pmax, p1[r]);
;   { auto rr = __builtin_amdgcn_permlane32_swap(__float_as_uint(pmax), __float_as_uint(pmax), false, false);
;     pmax = fmaxf(__uint_as_float(rr[0]), __uint_as_float(rr[1])); }
;   if (__builtin_expect(__all(pmax - m_reg <= THR / SCALE), 1)) { mn = m_reg; alpha = 1.f; }
;   else { mn = fmaxf(m_reg, pmax); alpha = __builtin_amdgcn_exp2f((m_reg - mn) * C); m_reg = mn; }
;   const float mnC = -mn * C;
; #pragma unroll
;   for (int r = 0; r < 16; ++r) p0[r] = fmaf(p0[r], C, mnC);
; #pragma unroll
;   for (int r = 0; r < 16; ++r) p1[r] = fmaf(p1[r], C, mnC);
; #pragma unroll
;   for (int r = 0; r < 16; ++r) p0[r] = __builtin_amdgcn_exp2f(p0[r]);
; }
; DI void finishSM(f32x16& p0, f32x16& p1, float alpha, float& l_reg, bf16x8& pa0, bf16x8& pa1, bf16x8& pa2, bf16x8& pa3) {
; #pragma unroll
;   for (int r = 0; r < 16; ++r) p1[r] = __builtin_amdgcn_exp2f(p1[r]);
;   float ps = 0;
; #pragma unroll
;   for (int r = 0; r < 16; ++r) ps += p0[r];
; #pragma unroll
;   for (int r = 0; r < 16; ++r) ps += p1[r];
;   { auto rr = __builtin_amdgcn_permlane32_swap(__float_as_uint(ps), __float_as_uint(ps), false, false);
;     ps = __uint_as_float(rr[0]) + __uint_as_float(rr[1]); }
;   l_reg = l_reg * alpha + ps;
;     ...
;   PK4(p0, 0, pa0); PK4(p0, 8, pa1); PK4(p1, 0, pa2); PK4(p1, 8, pa3);
;     ...
; }
; template <int DQK, int SDEPTH, bool OUT_BF16, int QREG = DQK / 16, bool OUT_F16 = false> ...
;     ...
;   SLOAD(SE, 0); asm volatile("s_waitcnt vmcnt(0)" ::: "memory"); SWRITE(0, SE); __syncthreads();
;   QKT(pA0, pA1, K_lds); partialSM(pA0, pA1, m_reg, mnA, alA, SCALE);
;   SLOAD(SO, KVBLK); if constexpr (SDEPTH == 2) { if (2 < NT) SLOAD(SE, 2 * KVBLK); }
;   SWAIT(); SWRITE(1, SO); __syncthreads();
	s_waitcnt vmcnt(4)
	ds_write_b128 v167, v[50:53] offset:16384
	s_waitcnt vmcnt(3)
	ds_write_b128 v168, v[54:57] offset:16384
	s_waitcnt vmcnt(2)
	ds_write_b128 v169, v[58:61] offset:57344
	s_waitcnt vmcnt(1)
	ds_write_b128 v170, v[62:65] offset:57344
	s_waitcnt vmcnt(0)
	ds_write_b128 v171, v[66:69] offset:57344
	s_cselect_b64 vcc, -1, 0
	v_max_f32_e32 v51, 0xf149f2ca, v87
	v_cndmask_b32_e32 v194, v51, v239, vcc
	v_mul_f32_e32 v50, 0xbf800000, v194
	v_fmamk_f32 v34, v34, 0x3f800000, v50
	v_exp_f32_e32 v134, v34
	v_fmamk_f32 v34, v35, 0x3f800000, v50
	v_exp_f32_e32 v135, v34
	v_fmamk_f32 v34, v36, 0x3f800000, v50
	v_exp_f32_e32 v136, v34
	v_fmamk_f32 v34, v37, 0x3f800000, v50
	v_exp_f32_e32 v138, v34
	v_fmamk_f32 v34, v38, 0x3f800000, v50
	v_exp_f32_e32 v155, v34
	v_fmamk_f32 v34, v39, 0x3f800000, v50
	v_exp_f32_e32 v156, v34
	v_fmamk_f32 v34, v40, 0x3f800000, v50
	v_exp_f32_e32 v137, v34
	v_fmamk_f32 v34, v41, 0x3f800000, v50
	v_pk_fma_f32 v[126:127], v[18:19], s[30:31], v[50:51] op_sel_hi:[1,0,0]
	v_sub_f32_e32 v18, 0xf149f2ca, v51
	v_exp_f32_e32 v154, v34
	v_fmamk_f32 v34, v42, 0x3f800000, v50
	v_mul_f32_e32 v18, 0x3f800000, v18
	v_exp_f32_e32 v131, v34
	v_fmamk_f32 v34, v43, 0x3f800000, v50
	v_exp_f32_e32 v18, v18
	v_exp_f32_e32 v133, v34
	v_fmamk_f32 v34, v44, 0x3f800000, v50
	v_exp_f32_e32 v139, v34
	v_fmamk_f32 v34, v45, 0x3f800000, v50
	v_exp_f32_e32 v152, v34
	v_fmamk_f32 v34, v46, 0x3f800000, v50
	s_add_i32 s2, 0, 0x4000
	v_exp_f32_e32 v132, v34
	v_fmamk_f32 v34, v47, 0x3f800000, v50
	v_cndmask_b32_e64 v197, v18, 1.0, vcc
	v_add_u32_e32 v165, s2, v86
	v_mad_i64_i32 v[18:19], s[2:3], s38, v240, v[80:81]
	v_exp_f32_e32 v140, v34
	v_fmamk_f32 v34, v48, 0x3f800000, v50
	v_lshl_add_u64 v[144:145], v[18:19], 0, v[82:83]
	v_mad_i64_i32 v[18:19], s[2:3], s38, v240, v[76:77]
	v_exp_f32_e32 v141, v34
	v_fmamk_f32 v34, v49, 0x3f800000, v50
	v_lshl_add_u64 v[146:147], v[18:19], 0, v[78:79]
	v_mad_i64_i32 v[18:19], s[2:3], s38, v240, v[72:73]
	v_exp_f32_e32 v153, v34
	v_lshl_add_u64 v[148:149], v[18:19], 0, v[74:75]
	v_mov_b32_e32 v18, 0x210000
	v_mad_i64_i32 v[150:151], s[2:3], s38, v18, v[70:71]
	v_and_b32_e32 v18, 15, v84
	v_pk_fma_f32 v[114:115], v[32:33], s[30:31], v[50:51] op_sel_hi:[1,0,0]
	v_pk_fma_f32 v[120:121], v[30:31], s[30:31], v[50:51] op_sel_hi:[1,0,0]
	v_pk_fma_f32 v[128:129], v[28:29], s[30:31], v[50:51] op_sel_hi:[1,0,0]
	v_pk_fma_f32 v[116:117], v[26:27], s[30:31], v[50:51] op_sel_hi:[1,0,0]
	v_pk_fma_f32 v[118:119], v[24:25], s[30:31], v[50:51] op_sel_hi:[1,0,0]
	v_pk_fma_f32 v[122:123], v[22:23], s[30:31], v[50:51] op_sel_hi:[1,0,0]
	v_pk_fma_f32 v[124:125], v[20:21], s[30:31], v[50:51] op_sel_hi:[1,0,0]
	v_lshl_or_b32 v150, v18, 4, v150
	v_mov_b64_e32 v[64:65], v[16:17]
	v_mov_b64_e32 v[48:49], v[16:17]
	v_mov_b64_e32 v[32:33], v[16:17]
	v_cmp_gt_u32_e64 s[0:1], 32, v85
	v_mov_b64_e32 v[62:63], v[14:15]
	v_mov_b64_e32 v[60:61], v[12:13]
	v_mov_b64_e32 v[58:59], v[10:11]
	v_mov_b64_e32 v[56:57], v[8:9]
	v_mov_b64_e32 v[54:55], v[6:7]
	v_mov_b64_e32 v[52:53], v[4:5]
	v_mov_b64_e32 v[50:51], v[2:3]
	v_mov_b64_e32 v[46:47], v[14:15]
	v_mov_b64_e32 v[44:45], v[12:13]
	v_mov_b64_e32 v[42:43], v[10:11]
	v_mov_b64_e32 v[40:41], v[8:9]
	v_mov_b64_e32 v[38:39], v[6:7]
	v_mov_b64_e32 v[36:37], v[4:5]
	v_mov_b64_e32 v[34:35], v[2:3]
	v_mov_b64_e32 v[30:31], v[14:15]
	v_mov_b64_e32 v[28:29], v[12:13]
	v_mov_b64_e32 v[26:27], v[10:11]
	v_mov_b64_e32 v[24:25], v[8:9]
	v_mov_b64_e32 v[22:23], v[6:7]
	v_mov_b64_e32 v[20:21], v[4:5]
	v_mov_b64_e32 v[18:19], v[2:3]
	s_waitcnt lgkmcnt(0)
	s_barrier
	s_add_u32 s80, s4, 0x4487c000
	s_addc_u32 s81, s5, 0
	s_add_u32 s82, s4, 0x4487e000
	s_addc_u32 s83, s5, 0
	s_add_u32 s84, s4, s97
	s_addc_u32 s85, s5, 0
	s_add_u32 s86, s4, 0x44880000
	s_addc_u32 s87, s5, 0
	s_add_u32 s88, s4, 0x44882000
	s_addc_u32 s89, s5, 0
	s_add_u32 s90, s4, s79
	s_addc_u32 s91, s5, 0
	v_exp_f32_e32 v126, v126
	v_exp_f32_e32 v127, v127
	v_exp_f32_e32 v124, v124
	v_exp_f32_e32 v125, v125
	v_exp_f32_e32 v122, v122
	v_exp_f32_e32 v123, v123
	v_exp_f32_e32 v118, v118
	v_exp_f32_e32 v119, v119
	v_exp_f32_e32 v116, v116
	v_exp_f32_e32 v117, v117
	v_exp_f32_e32 v128, v128
	v_exp_f32_e32 v129, v129
	v_exp_f32_e32 v120, v120
	v_exp_f32_e32 v121, v121
	v_exp_f32_e32 v114, v114
	v_exp_f32_e32 v115, v115
	v_mul_f32_e32 v226, 0xbf800000, v194
	v_add_f32_e32 v97, v134, v135
	v_add_f32_e32 v97, v136, v97
	v_add_f32_e32 v97, v138, v97
	v_add_f32_e32 v97, v155, v97
	v_add_f32_e32 v97, v156, v97
	v_add_f32_e32 v97, v137, v97
	v_add_f32_e32 v97, v154, v97
	v_add_f32_e32 v97, v131, v97
	v_add_f32_e32 v97, v133, v97
	v_add_f32_e32 v97, v139, v97
	v_add_f32_e32 v97, v152, v97
	v_add_f32_e32 v97, v132, v97
	v_add_f32_e32 v97, v140, v97
	v_add_f32_e32 v97, v141, v97
	v_add_f32_e32 v97, v153, v97
	v_add_f32_e32 v97, v126, v97
	v_add_f32_e32 v97, v127, v97
	v_add_f32_e32 v97, v124, v97
	v_add_f32_e32 v97, v125, v97
	v_add_f32_e32 v97, v122, v97
	v_add_f32_e32 v97, v123, v97
	v_add_f32_e32 v97, v118, v97
	v_add_f32_e32 v97, v119, v97
	v_add_f32_e32 v97, v116, v97
	v_add_f32_e32 v97, v117, v97
	v_add_f32_e32 v97, v128, v97
	v_add_f32_e32 v97, v129, v97
	v_add_f32_e32 v97, v120, v97
	v_add_f32_e32 v97, v121, v97
	v_add_f32_e32 v97, v114, v97
	v_add_f32_e32 v97, v115, v97
	v_cvt_pk_bf16_f32 v66, v134, v135
	v_cvt_pk_bf16_f32 v67, v136, v138
	v_cvt_pk_bf16_f32 v68, v155, v156
	v_cvt_pk_bf16_f32 v69, v137, v154
	v_cvt_pk_bf16_f32 v70, v131, v133
	v_cvt_pk_bf16_f32 v71, v139, v152
	v_cvt_pk_bf16_f32 v72, v132, v140
	v_cvt_pk_bf16_f32 v73, v141, v153
	v_cvt_pk_bf16_f32 v74, v126, v127
	v_cvt_pk_bf16_f32 v75, v124, v125
	v_cvt_pk_bf16_f32 v76, v122, v123
; #define SBAR() __builtin_amdgcn_sched_barrier(0)
; #define SLOAD(i, k0) do { sr_[i].vs0 = *reinterpret_cast<const bf16x8*>(&Vh[(long)((k0) + sr) * DV + sc]); sr_[i].vs1 = *reinterpret_cast<const bf16x8*>(&Vh[(long)((k0) + 32 + sr) * DV + sc]); \
;     _Pragma("unroll") for (int _c = 0; _c < NKC; ++_c) sr_[i].ks[_c] = *reinterpret_cast<const bf16x8*>(&Kh[(long)((k0) + krow[_c]) * DQK + kcol[_c]]); } while (0)
; DI void finishSM(f32x16& p0, f32x16& p1, float alpha, float& l_reg, bf16x8& pa0, bf16x8& pa1, bf16x8& pa2, bf16x8& pa3) {
;     ...
;   PK4(p0, 0, pa0); PK4(p0, 8, pa1); PK4(p1, 0, pa2); PK4(p1, 8, pa3);
; template <int DQK, int SDEPTH, bool OUT_BF16, int QREG = DQK / 16, bool OUT_F16 = false> ...
;     ...
;   for (int j = 1; j + 1 < NT; j += 2) {
;     SBAR(); QKT(pB0, pB1, K_lds + SHM_K);
;     finishSM(pA0, pA1, alA, l_reg, pa0, pa1, pa2, pa3); SBAR();
;     SLOAD(SO, (j + SDEPTH) * KVBLK); SBAR();
;     pv_d0(o, vb0, pa0, pa1, pa2, pa3); partialSM(pB0, pB1, m_reg, mnB, alB, SCALE);
	v_cvt_pk_bf16_f32 v77, v118, v119
	v_cvt_pk_bf16_f32 v78, v116, v117
	v_cvt_pk_bf16_f32 v79, v128, v129
	v_cvt_pk_bf16_f32 v80, v120, v121
	v_cvt_pk_bf16_f32 v81, v114, v115
	v_bfe_u32 v96, v163, 8, 1
	v_mul_u32_u24_e32 v96, 0x700, v96
	v_add_u32_e32 v163, v163, v96
	v_add_u32_e32 v165, v165, v96
	v_mov_b32_e32 v134, v66
	v_mov_b32_e32 v135, v67
	v_mov_b32_e32 v136, v68
	v_mov_b32_e32 v137, v69
	v_mov_b32_e32 v138, v70
	v_mov_b32_e32 v139, v71
	v_mov_b32_e32 v140, v72
	v_mov_b32_e32 v141, v73
	v_mov_b32_e32 v214, v74
	v_mov_b32_e32 v215, v75
	v_mov_b32_e32 v216, v76
	v_mov_b32_e32 v217, v77
	v_mov_b32_e32 v218, v78
	v_mov_b32_e32 v219, v79
	v_mov_b32_e32 v220, v80
	v_mov_b32_e32 v221, v81
	v_mov_b32_e32 v166, v97
	v_mov_b32_e32 v184, v226
	v_mov_b32_e32 v185, v226
	v_mov_b32_e32 v186, v226
	v_mov_b32_e32 v187, v226
	v_mov_b32_e32 v188, v226
	v_mov_b32_e32 v189, v226
	v_mov_b32_e32 v190, v226
	v_mov_b32_e32 v191, v226
	v_mov_b32_e32 v192, v226
	v_mov_b32_e32 v193, v226
	v_mov_b32_e32 v194, v226
	v_mov_b32_e32 v195, v226
	v_mov_b32_e32 v196, v226
	v_mov_b32_e32 v197, v226
	v_mov_b32_e32 v198, v226
	v_mov_b32_e32 v199, v226
	v_add_u32_e32 v172, 0x3000, v172
	v_add_u32_e32 v173, 0x3000, v173
	v_add_u32_e32 v174, 0x3000, v174
	v_add_u32_e32 v175, 0x3000, v175
	v_add_u32_e32 v176, 0x3000, v176
	v_add_u32_e32 v177, 0x3000, v177
	v_add_u32_e32 v178, 0x3000, v178
	v_add_u32_e32 v179, 0x3000, v179
	v_add_u32_e32 v180, 0x3000, v180
	v_add_u32_e32 v181, 0x3000, v181
	v_add_u32_e32 v182, 0x3000, v182
	v_add_u32_e32 v183, 0x3000, v183
	global_load_dwordx4 v[114:117], v150, s[80:81]
	global_load_dwordx4 v[118:121], v150, s[82:83]
	global_load_dwordx4 v[122:125], v148, s[84:85]
	global_load_dwordx4 v[126:129], v146, s[84:85]
	global_load_dwordx4 v[130:133], v144, s[84:85]
.LBB0_748:
	ds_read_b128 v[66:69], v172 offset:45056
	ds_read_b128 v[70:73], v172 offset:57344
	ds_read_b128 v[244:247], v173 offset:45056
	ds_read_b128 v[202:205], v173 offset:57344
	s_waitcnt lgkmcnt(3)
	v_mfma_f32_32x32x16_bf16 v[82:97], v[66:69], v[110:113], v[184:199]
	s_waitcnt lgkmcnt(2)
	v_mfma_f32_32x32x16_bf16 v[66:81], v[70:73], v[110:113], v[184:199]
	s_waitcnt lgkmcnt(1)
	v_mfma_f32_32x32x16_bf16 v[82:97], v[244:247], v[106:109], v[82:97]
	s_waitcnt lgkmcnt(0)
	v_mfma_f32_32x32x16_bf16 v[66:81], v[202:205], v[106:109], v[66:81]
	ds_read_b128 v[244:247], v174 offset:45056
	ds_read_b128 v[202:205], v174 offset:57344
	s_waitcnt lgkmcnt(1)
	v_mfma_f32_32x32x16_bf16 v[82:97], v[244:247], v[102:105], v[82:97]
	s_waitcnt lgkmcnt(0)
	v_mfma_f32_32x32x16_bf16 v[66:81], v[202:205], v[102:105], v[66:81]
	ds_read_b128 v[244:247], v175 offset:45056
	ds_read_b128 v[202:205], v175 offset:57344
	s_waitcnt lgkmcnt(1)
	v_mfma_f32_32x32x16_bf16 v[82:97], v[244:247], v[98:101], v[82:97]
	s_waitcnt lgkmcnt(0)
	v_mfma_f32_32x32x16_bf16 v[66:81], v[202:205], v[98:101], v[66:81]
	ds_read_b128 v[244:247], v176 offset:45056
	ds_read_b128 v[202:205], v176 offset:57344
	ds_read_b128 v[206:209], v162
	s_waitcnt lgkmcnt(0)
	v_mfma_f32_32x32x16_bf16 v[82:97], v[244:247], v[206:209], v[82:97]
	v_mfma_f32_32x32x16_bf16 v[66:81], v[202:205], v[206:209], v[66:81]
	ds_read_b128 v[244:247], v177 offset:45056
	ds_read_b128 v[202:205], v177 offset:57344
	ds_read_b128 v[206:209], v162 offset:1024
	s_waitcnt lgkmcnt(0)
	v_mfma_f32_32x32x16_bf16 v[82:97], v[244:247], v[206:209], v[82:97]
	v_mfma_f32_32x32x16_bf16 v[66:81], v[202:205], v[206:209], v[66:81]
	ds_read_b128 v[244:247], v178 offset:45056
	ds_read_b128 v[202:205], v178 offset:57344
	ds_read_b128 v[206:209], v162 offset:2048
	s_waitcnt lgkmcnt(0)
	v_mfma_f32_32x32x16_bf16 v[82:97], v[244:247], v[206:209], v[82:97]
	v_mfma_f32_32x32x16_bf16 v[66:81], v[202:205], v[206:209], v[66:81]
	ds_read_b128 v[244:247], v179 offset:45056
	ds_read_b128 v[202:205], v179 offset:57344
	ds_read_b128 v[206:209], v162 offset:3072
	s_waitcnt lgkmcnt(0)
	v_mfma_f32_32x32x16_bf16 v[82:97], v[244:247], v[206:209], v[82:97]
	v_mfma_f32_32x32x16_bf16 v[66:81], v[202:205], v[206:209], v[66:81]
	ds_read_b128 v[244:247], v180 offset:45056
	ds_read_b128 v[202:205], v180 offset:57344
	ds_read_b128 v[206:209], v162 offset:4096
	s_waitcnt lgkmcnt(0)
	v_mfma_f32_32x32x16_bf16 v[82:97], v[244:247], v[206:209], v[82:97]
	v_mfma_f32_32x32x16_bf16 v[66:81], v[202:205], v[206:209], v[66:81]
	ds_read_b128 v[244:247], v181 offset:45056
	ds_read_b128 v[202:205], v181 offset:57344
	ds_read_b128 v[206:209], v162 offset:5120
	s_waitcnt lgkmcnt(0)
	v_mfma_f32_32x32x16_bf16 v[82:97], v[244:247], v[206:209], v[82:97]
	v_mfma_f32_32x32x16_bf16 v[66:81], v[202:205], v[206:209], v[66:81]
	ds_read_b128 v[244:247], v182 offset:45056
	ds_read_b128 v[202:205], v182 offset:57344
	ds_read_b128 v[206:209], v162 offset:6144
	s_waitcnt lgkmcnt(0)
	v_mfma_f32_32x32x16_bf16 v[82:97], v[244:247], v[206:209], v[82:97]
	v_mfma_f32_32x32x16_bf16 v[66:81], v[202:205], v[206:209], v[66:81]
	ds_read_b128 v[244:247], v183 offset:45056
	ds_read_b128 v[202:205], v183 offset:57344
	ds_read_b128 v[206:209], v162 offset:7168
	s_waitcnt lgkmcnt(0)
	v_mfma_f32_32x32x16_bf16 v[82:97], v[244:247], v[206:209], v[82:97]
	v_mfma_f32_32x32x16_bf16 v[66:81], v[202:205], v[206:209], v[66:81]
	ds_read_b64_tr_b16 v[200:201], v163 offset:0x0
	ds_read_b64_tr_b16 v[202:203], v163 offset:0x100
	ds_read_b64_tr_b16 v[204:205], v163 offset:0x1000
	ds_read_b64_tr_b16 v[206:207], v163 offset:0x1100
	ds_read_b64_tr_b16 v[208:209], v163 offset:0x2000
	ds_read_b64_tr_b16 v[210:211], v163 offset:0x2100
	ds_read_b64_tr_b16 v[222:223], v163 offset:0x3000
	ds_read_b64_tr_b16 v[224:225], v163 offset:0x3100
	s_waitcnt lgkmcnt(0)
; #define LAS __attribute__((address_space(3)))
; DI void finishSM(f32x16& p0, f32x16& p1, float alpha, float& l_reg, bf16x8& pa0, bf16x8& pa1, bf16x8& pa2, bf16x8& pa3) {
; #pragma unroll
;   for (int r = 0; r < 16; ++r) p1[r] = __builtin_amdgcn_exp2f(p1[r]);
;   float ps = 0;
; #pragma unroll
;   for (int r = 0; r < 16; ++r) ps += p0[r];
; #pragma unroll
;   for (int r = 0; r < 16; ++r) ps += p1[r];
;   { auto rr = __builtin_amdgcn_permlane32_swap(__float_as_uint(ps), __float_as_uint(ps), false, false);
;     ps = __uint_as_float(rr[0]) + __uint_as_float(rr[1]); }
;   l_reg = l_reg * alpha + ps;
;     ...
;   PK4(p0, 0, pa0); PK4(p0, 8, pa1); PK4(p1, 0, pa2); PK4(p1, 8, pa3);
;     ...
; }
; template <int DQK> DI void qkt(f32x16& p0, f32x16& p1, const LAS char* Ks, const bf16x8* qr, int r32, int hi) {
;   p0 = f32x16{}; p1 = f32x16{};
; #pragma unroll
;   for (int d0 = 0; d0 < DQK / 16; ++d0) { const int cb = (d0 * 16 + hi * 8) * 2;
;     const bf16x8 b0 = *(const LAS bf16x8*)(Ks + kswz<DQK>(r32, cb));
;     const bf16x8 b1 = *(const LAS bf16x8*)(Ks + kswz<DQK>(32 + r32, cb));
;     p0 = __builtin_amdgcn_mfma_f32_32x32x16_bf16(b0, qr[d0], p0, 0, 0, 0);
;     p1 = __builtin_amdgcn_mfma_f32_32x32x16_bf16(b1, qr[d0], p1, 0, 0, 0); }
; }
; DI int v_st(int k, int c) { const int kk = (k & ~0xC) | ((k & 4) << 1) | ((k & 8) >> 1); return ((kk >> 3) * 4 + (c >> 5)) * 512 + ((kk & 7) * 32 + (c & 31)) * 2; }
; DI int v_rd_base(int lane) { return ((lane & 3) << 3) | (((lane >> 2) & 3) << 6) | (((lane >> 4) & 1) << 5) | (((lane >> 5) & 1) << 8); }
; template <int OFF> DI s16x4 tr_read(int vb) { s16x4 r; asm volatile("ds_read_b64_tr_b16 %0, %1 offset:%2" : "=&v"(r) : "v"(vb), "i"(OFF) : "memory"); return r; }
; template <int D0> DI void pv_one(f32x16& od, int vb, bf16x8 pa0, bf16x8 pa1, bf16x8 pa2, bf16x8 pa3) {
;   const s16x4 l0 = tr_read<v_rd_off(D0, 0, 0)>(vb), h0 = tr_read<v_rd_off(D0, 0, 1)>(vb), l1 = tr_read<v_rd_off(D0, 1, 0)>(vb), h1 = tr_read<v_rd_off(D0, 1, 1)>(vb);
;   const s16x4 l2 = tr_read<v_rd_off(D0, 2, 0)>(vb), h2 = tr_read<v_rd_off(D0, 2, 1)>(vb), l3 = tr_read<v_rd_off(D0, 3, 0)>(vb), h3 = tr_read<v_rd_off(D0, 3, 1)>(vb);
;   asm volatile("s_waitcnt lgkmcnt(0)" ::: "memory"); SBAR();
;     ...
;   od = __builtin_amdgcn_mfma_f32_32x32x16_bf16(pa0, PK(l0, h0), od, 0, 0, 0);
;   od = __builtin_amdgcn_mfma_f32_32x32x16_bf16(pa1, PK(l1, h1), od, 0, 0, 0);
	v_mfma_f32_32x32x16_bf16 v[2:17], v[134:137], v[200:203], v[2:17]
	ds_read_b64_tr_b16 v[200:201], v163 offset:0x200
	ds_read_b64_tr_b16 v[202:203], v163 offset:0x300
	v_exp_f32_e32 v82, v82
	v_exp_f32_e32 v83, v83
	v_exp_f32_e32 v84, v84
	v_exp_f32_e32 v85, v85
	v_exp_f32_e32 v86, v86
	v_mfma_f32_32x32x16_bf16 v[2:17], v[138:141], v[204:207], v[2:17]
	ds_read_b64_tr_b16 v[204:205], v163 offset:0x1200
	ds_read_b64_tr_b16 v[206:207], v163 offset:0x1300
	v_add_f32_e32 v252, v82, v83
	v_exp_f32_e32 v87, v87
	v_add_f32_e32 v252, v84, v252
	v_exp_f32_e32 v88, v88
	v_add_f32_e32 v252, v85, v252
	v_mfma_f32_32x32x16_bf16 v[2:17], v[214:217], v[208:211], v[2:17]
	ds_read_b64_tr_b16 v[208:209], v163 offset:0x2200
	ds_read_b64_tr_b16 v[210:211], v163 offset:0x2300
	v_cvt_pk_bf16_f32 v152, v82, v83
	v_exp_f32_e32 v89, v89
	v_add_f32_e32 v252, v86, v252
	v_exp_f32_e32 v90, v90
	v_add_f32_e32 v252, v87, v252
	v_mfma_f32_32x32x16_bf16 v[2:17], v[218:221], v[222:225], v[2:17]
	ds_read_b64_tr_b16 v[222:223], v163 offset:0x3200
	ds_read_b64_tr_b16 v[224:225], v163 offset:0x3300
	v_cvt_pk_bf16_f32 v153, v84, v85
	v_exp_f32_e32 v91, v91
	v_add_f32_e32 v252, v88, v252
	v_exp_f32_e32 v92, v92
	v_add_f32_e32 v252, v89, v252
	s_waitcnt lgkmcnt(0)
	v_mfma_f32_32x32x16_bf16 v[50:65], v[134:137], v[200:203], v[50:65]
	ds_read_b64_tr_b16 v[200:201], v163 offset:0x400
	ds_read_b64_tr_b16 v[202:203], v163 offset:0x500
	v_cvt_pk_bf16_f32 v154, v86, v87
	v_exp_f32_e32 v93, v93
	v_add_f32_e32 v252, v90, v252
	v_exp_f32_e32 v94, v94
	v_add_f32_e32 v252, v91, v252
	v_mfma_f32_32x32x16_bf16 v[50:65], v[138:141], v[204:207], v[50:65]
	ds_read_b64_tr_b16 v[204:205], v163 offset:0x1400
	ds_read_b64_tr_b16 v[206:207], v163 offset:0x1500
	v_cvt_pk_bf16_f32 v155, v88, v89
	v_exp_f32_e32 v95, v95
	v_add_f32_e32 v252, v92, v252
	v_exp_f32_e32 v96, v96
	v_add_f32_e32 v252, v93, v252
	v_mfma_f32_32x32x16_bf16 v[50:65], v[214:217], v[208:211], v[50:65]
	ds_read_b64_tr_b16 v[208:209], v163 offset:0x2400
	ds_read_b64_tr_b16 v[210:211], v163 offset:0x2500
	v_cvt_pk_bf16_f32 v156, v90, v91
	v_exp_f32_e32 v97, v97
	v_add_f32_e32 v252, v94, v252
	v_exp_f32_e32 v66, v66
	v_add_f32_e32 v252, v95, v252
	v_mfma_f32_32x32x16_bf16 v[50:65], v[218:221], v[222:225], v[50:65]
	ds_read_b64_tr_b16 v[222:223], v163 offset:0x3400
	ds_read_b64_tr_b16 v[224:225], v163 offset:0x3500
	v_cvt_pk_bf16_f32 v157, v92, v93
	v_exp_f32_e32 v67, v67
	v_add_f32_e32 v252, v96, v252
	v_exp_f32_e32 v68, v68
	v_add_f32_e32 v252, v97, v252
	s_waitcnt lgkmcnt(0)
	v_mfma_f32_32x32x16_bf16 v[34:49], v[134:137], v[200:203], v[34:49]
	ds_read_b64_tr_b16 v[200:201], v163 offset:0x600
	ds_read_b64_tr_b16 v[202:203], v163 offset:0x700
	v_cvt_pk_bf16_f32 v158, v94, v95
	v_exp_f32_e32 v69, v69
	v_add_f32_e32 v252, v66, v252
	v_exp_f32_e32 v70, v70
	v_add_f32_e32 v252, v67, v252
	v_cvt_pk_bf16_f32 v159, v96, v97
	v_mfma_f32_32x32x16_bf16 v[34:49], v[138:141], v[204:207], v[34:49]
	ds_read_b64_tr_b16 v[204:205], v163 offset:0x1600
	ds_read_b64_tr_b16 v[206:207], v163 offset:0x1700
	v_exp_f32_e32 v71, v71
	v_add_f32_e32 v252, v68, v252
	v_exp_f32_e32 v72, v72
	v_add_f32_e32 v252, v69, v252
	v_cvt_pk_bf16_f32 v228, v66, v67
	v_mfma_f32_32x32x16_bf16 v[34:49], v[214:217], v[208:211], v[34:49]
	ds_read_b64_tr_b16 v[208:209], v163 offset:0x2600
	ds_read_b64_tr_b16 v[210:211], v163 offset:0x2700
	v_exp_f32_e32 v73, v73
	v_add_f32_e32 v252, v70, v252
	v_exp_f32_e32 v74, v74
	v_add_f32_e32 v252, v71, v252
	v_cvt_pk_bf16_f32 v229, v68, v69
	v_mfma_f32_32x32x16_bf16 v[34:49], v[218:221], v[222:225], v[34:49]
	ds_read_b64_tr_b16 v[222:223], v163 offset:0x3600
	ds_read_b64_tr_b16 v[224:225], v163 offset:0x3700
	v_exp_f32_e32 v75, v75
	v_add_f32_e32 v252, v72, v252
	v_exp_f32_e32 v76, v76
	v_add_f32_e32 v252, v73, v252
	v_cvt_pk_bf16_f32 v230, v70, v71
	s_waitcnt lgkmcnt(0)
	v_mfma_f32_32x32x16_bf16 v[18:33], v[134:137], v[200:203], v[18:33]
	v_exp_f32_e32 v77, v77
	v_add_f32_e32 v252, v74, v252
	v_exp_f32_e32 v78, v78
	v_add_f32_e32 v252, v75, v252
	v_cvt_pk_bf16_f32 v231, v72, v73
	v_mfma_f32_32x32x16_bf16 v[18:33], v[138:141], v[204:207], v[18:33]
	v_exp_f32_e32 v79, v79
	v_add_f32_e32 v252, v76, v252
	v_exp_f32_e32 v80, v80
	v_add_f32_e32 v252, v77, v252
	v_cvt_pk_bf16_f32 v248, v74, v75
	v_mfma_f32_32x32x16_bf16 v[18:33], v[214:217], v[208:211], v[18:33]
	v_exp_f32_e32 v81, v81
	v_add_f32_e32 v252, v78, v252
	v_add_f32_e32 v252, v79, v252
	v_cvt_pk_bf16_f32 v249, v76, v77
	v_add_f32_e32 v252, v80, v252
	v_mfma_f32_32x32x16_bf16 v[18:33], v[218:221], v[222:225], v[18:33]
	v_add_f32_e32 v252, v81, v252
	v_cvt_pk_bf16_f32 v250, v78, v79
	v_cvt_pk_bf16_f32 v251, v80, v81
	v_cmp_nge_f32_e32 vcc, 0x453a4f54, v252
	v_add_f32_e32 v227, v166, v252
	s_barrier
	s_waitcnt vmcnt(0)
	ds_write_b128 v167, v[114:117]
	ds_write_b128 v168, v[118:121]
	ds_write_b128 v169, v[122:125] offset:32768
	ds_write_b128 v170, v[126:129] offset:32768
	ds_write_b128 v171, v[130:133] offset:32768
	global_load_dwordx4 v[114:117], v150, s[86:87]
	global_load_dwordx4 v[118:121], v150, s[88:89]
	global_load_dwordx4 v[122:125], v148, s[90:91]
	global_load_dwordx4 v[126:129], v146, s[90:91]
	global_load_dwordx4 v[130:133], v144, s[90:91]
	s_cbranch_vccz .LBB0_752
; DI void partialSM(f32x16& p0, f32x16& p1, float& m_reg, float& mn, float& alpha, const float SCALE) {
;   const float C = SCALE * 1.4426950408889634f;
;   float pmax = p0[0];
; #pragma unroll
;   for (int r = 1; r < 16; ++r) pmax = fmaxf(pmax, p0[r]);
; #pragma unroll
;   for (int r = 0; r < 16; ++r) pmax = fmaxf(pmax, p1[r]);
;   { auto rr = __builtin_amdgcn_permlane32_swap(__float_as_uint(pmax), __float_as_uint(pmax), false, false);
;     pmax = fmaxf(__uint_as_float(rr[0]), __uint_as_float(rr[1])); }
;   if (__builtin_expect(__all(pmax - m_reg <= THR / SCALE), 1)) { mn = m_reg; alpha = 1.f; }
;   else { mn = fmaxf(m_reg, pmax); alpha = __builtin_amdgcn_exp2f((m_reg - mn) * C); m_reg = mn; }
;   const float mnC = -mn * C;
; #pragma unroll
;   for (int r = 0; r < 16; ++r) p0[r] = fmaf(p0[r], C, mnC);
; #pragma unroll
;   for (int r = 0; r < 16; ++r) p1[r] = fmaf(p1[r], C, mnC);
; #pragma unroll
;   for (int r = 0; r < 16; ++r) p0[r] = __builtin_amdgcn_exp2f(p0[r]);
; }
	ds_read_b128 v[66:69], v172 offset:45056
	ds_read_b128 v[70:73], v172 offset:57344
	ds_read_b128 v[244:247], v173 offset:45056
	ds_read_b128 v[202:205], v173 offset:57344
	s_waitcnt lgkmcnt(3)
	v_mfma_f32_32x32x16_bf16 v[82:97], v[66:69], v[110:113], 0
	s_waitcnt lgkmcnt(2)
	v_mfma_f32_32x32x16_bf16 v[66:81], v[70:73], v[110:113], 0
	s_waitcnt lgkmcnt(1)
	v_mfma_f32_32x32x16_bf16 v[82:97], v[244:247], v[106:109], v[82:97]
	s_waitcnt lgkmcnt(0)
	v_mfma_f32_32x32x16_bf16 v[66:81], v[202:205], v[106:109], v[66:81]
	ds_read_b128 v[244:247], v174 offset:45056
	ds_read_b128 v[202:205], v174 offset:57344
	s_waitcnt lgkmcnt(1)
	v_mfma_f32_32x32x16_bf16 v[82:97], v[244:247], v[102:105], v[82:97]
	s_waitcnt lgkmcnt(0)
	v_mfma_f32_32x32x16_bf16 v[66:81], v[202:205], v[102:105], v[66:81]
	ds_read_b128 v[244:247], v175 offset:45056
	ds_read_b128 v[202:205], v175 offset:57344
	s_waitcnt lgkmcnt(1)
	v_mfma_f32_32x32x16_bf16 v[82:97], v[244:247], v[98:101], v[82:97]
	s_waitcnt lgkmcnt(0)
	v_mfma_f32_32x32x16_bf16 v[66:81], v[202:205], v[98:101], v[66:81]
	ds_read_b128 v[244:247], v176 offset:45056
	ds_read_b128 v[202:205], v176 offset:57344
	ds_read_b128 v[206:209], v162
	s_waitcnt lgkmcnt(0)
	v_mfma_f32_32x32x16_bf16 v[82:97], v[244:247], v[206:209], v[82:97]
	v_mfma_f32_32x32x16_bf16 v[66:81], v[202:205], v[206:209], v[66:81]
	ds_read_b128 v[244:247], v177 offset:45056
	ds_read_b128 v[202:205], v177 offset:57344
	ds_read_b128 v[206:209], v162 offset:1024
	s_waitcnt lgkmcnt(0)
	v_mfma_f32_32x32x16_bf16 v[82:97], v[244:247], v[206:209], v[82:97]
	v_mfma_f32_32x32x16_bf16 v[66:81], v[202:205], v[206:209], v[66:81]
	ds_read_b128 v[244:247], v178 offset:45056
	ds_read_b128 v[202:205], v178 offset:57344
	ds_read_b128 v[206:209], v162 offset:2048
	s_waitcnt lgkmcnt(0)
	v_mfma_f32_32x32x16_bf16 v[82:97], v[244:247], v[206:209], v[82:97]
	v_mfma_f32_32x32x16_bf16 v[66:81], v[202:205], v[206:209], v[66:81]
	ds_read_b128 v[244:247], v179 offset:45056
	ds_read_b128 v[202:205], v179 offset:57344
	ds_read_b128 v[206:209], v162 offset:3072
	s_waitcnt lgkmcnt(0)
	v_mfma_f32_32x32x16_bf16 v[82:97], v[244:247], v[206:209], v[82:97]
	v_mfma_f32_32x32x16_bf16 v[66:81], v[202:205], v[206:209], v[66:81]
	ds_read_b128 v[244:247], v180 offset:45056
	ds_read_b128 v[202:205], v180 offset:57344
	ds_read_b128 v[206:209], v162 offset:4096
	s_waitcnt lgkmcnt(0)
	v_mfma_f32_32x32x16_bf16 v[82:97], v[244:247], v[206:209], v[82:97]
	v_mfma_f32_32x32x16_bf16 v[66:81], v[202:205], v[206:209], v[66:81]
	ds_read_b128 v[244:247], v181 offset:45056
	ds_read_b128 v[202:205], v181 offset:57344
	ds_read_b128 v[206:209], v162 offset:5120
	s_waitcnt lgkmcnt(0)
	v_mfma_f32_32x32x16_bf16 v[82:97], v[244:247], v[206:209], v[82:97]
	v_mfma_f32_32x32x16_bf16 v[66:81], v[202:205], v[206:209], v[66:81]
	ds_read_b128 v[244:247], v182 offset:45056
	ds_read_b128 v[202:205], v182 offset:57344
	ds_read_b128 v[206:209], v162 offset:6144
	s_waitcnt lgkmcnt(0)
	v_mfma_f32_32x32x16_bf16 v[82:97], v[244:247], v[206:209], v[82:97]
	v_mfma_f32_32x32x16_bf16 v[66:81], v[202:205], v[206:209], v[66:81]
	ds_read_b128 v[244:247], v183 offset:45056
	ds_read_b128 v[202:205], v183 offset:57344
	ds_read_b128 v[206:209], v162 offset:7168
	s_waitcnt lgkmcnt(0)
	v_mfma_f32_32x32x16_bf16 v[82:97], v[244:247], v[206:209], v[82:97]
	v_mfma_f32_32x32x16_bf16 v[66:81], v[202:205], v[206:209], v[66:81]
	s_nop 7
	s_nop 7
	v_max3_f32 v244, v82, v83, v84
	v_max3_f32 v245, v85, v86, v87
	v_max3_f32 v244, v244, v88, v89
	v_max3_f32 v245, v245, v90, v91
	v_max3_f32 v244, v244, v92, v93
	v_max3_f32 v245, v245, v94, v95
	v_max3_f32 v244, v244, v96, v97
	v_max3_f32 v245, v245, v66, v67
	v_max3_f32 v244, v244, v68, v69
	v_max3_f32 v245, v245, v70, v71
	v_max3_f32 v244, v244, v72, v73
	v_max3_f32 v245, v245, v74, v75
	v_max3_f32 v244, v244, v76, v77
	v_max3_f32 v245, v245, v78, v79
	v_max3_f32 v244, v244, v80, v81
	v_max_f32_e32 v244, v244, v245
	v_mov_b32_e32 v245, v244
	s_nop 1
	v_permlane32_swap_b32_e32 v244, v245
	v_max_f32_e32 v244, v244, v245
	v_max_f32_e64 v244, -v226, v244
	v_sub_f32_e64 v245, -v226, v244
	v_exp_f32_e32 v200, v245
	v_mul_f32_e32 v226, 0xbf800000, v244
	v_mov_b32_e32 v184, v226
	v_mov_b32_e32 v185, v226
	v_mov_b32_e32 v186, v226
	v_mov_b32_e32 v187, v226
	v_mov_b32_e32 v188, v226
	v_mov_b32_e32 v189, v226
	v_mov_b32_e32 v190, v226
	v_mov_b32_e32 v191, v226
	v_mov_b32_e32 v192, v226
	v_mov_b32_e32 v193, v226
	v_mov_b32_e32 v194, v226
	v_mov_b32_e32 v195, v226
	v_mov_b32_e32 v196, v226
	v_mov_b32_e32 v197, v226
	v_mov_b32_e32 v198, v226
	v_mov_b32_e32 v199, v226
	v_add_f32_e32 v82, v226, v82
	v_add_f32_e32 v83, v226, v83
	v_add_f32_e32 v84, v226, v84
	v_add_f32_e32 v85, v226, v85
	v_add_f32_e32 v86, v226, v86
	v_add_f32_e32 v87, v226, v87
	v_add_f32_e32 v88, v226, v88
	v_add_f32_e32 v89, v226, v89
	v_add_f32_e32 v90, v226, v90
	v_add_f32_e32 v91, v226, v91
	v_add_f32_e32 v92, v226, v92
	v_add_f32_e32 v93, v226, v93
	v_add_f32_e32 v94, v226, v94
	v_add_f32_e32 v95, v226, v95
	v_add_f32_e32 v96, v226, v96
	v_add_f32_e32 v97, v226, v97
	v_add_f32_e32 v66, v226, v66
	v_add_f32_e32 v67, v226, v67
	v_add_f32_e32 v68, v226, v68
	v_add_f32_e32 v69, v226, v69
	v_add_f32_e32 v70, v226, v70
	v_add_f32_e32 v71, v226, v71
	v_add_f32_e32 v72, v226, v72
	v_add_f32_e32 v73, v226, v73
	v_add_f32_e32 v74, v226, v74
	v_add_f32_e32 v75, v226, v75
	v_add_f32_e32 v76, v226, v76
	v_add_f32_e32 v77, v226, v77
	v_add_f32_e32 v78, v226, v78
	v_add_f32_e32 v79, v226, v79
	v_add_f32_e32 v80, v226, v80
	v_add_f32_e32 v81, v226, v81
	v_exp_f32_e32 v82, v82
	v_exp_f32_e32 v83, v83
	v_exp_f32_e32 v84, v84
	v_exp_f32_e32 v85, v85
	v_exp_f32_e32 v86, v86
; #define SBAR() __builtin_amdgcn_sched_barrier(0)
; #define SLOAD(i, k0) do { sr_[i].vs0 = *reinterpret_cast<const bf16x8*>(&Vh[(long)((k0) + sr) * DV + sc]); sr_[i].vs1 = *reinterpret_cast<const bf16x8*>(&Vh[(long)((k0) + 32 + sr) * DV + sc]); \
;     _Pragma("unroll") for (int _c = 0; _c < NKC; ++_c) sr_[i].ks[_c] = *reinterpret_cast<const bf16x8*>(&Kh[(long)((k0) + krow[_c]) * DQK + kcol[_c]]); } while (0)
; DI void finishSM(f32x16& p0, f32x16& p1, float alpha, float& l_reg, bf16x8& pa0, bf16x8& pa1, bf16x8& pa2, bf16x8& pa3) {
; #pragma unroll
;   for (int r = 0; r < 16; ++r) p1[r] = __builtin_amdgcn_exp2f(p1[r]);
;   float ps = 0;
; #pragma unroll
;   for (int r = 0; r < 16; ++r) ps += p0[r];
; #pragma unroll
;   for (int r = 0; r < 16; ++r) ps += p1[r];
;   { auto rr = __builtin_amdgcn_permlane32_swap(__float_as_uint(ps), __float_as_uint(ps), false, false);
;     ps = __uint_as_float(rr[0]) + __uint_as_float(rr[1]); }
;   l_reg = l_reg * alpha + ps;
;     ...
;   PK4(p0, 0, pa0); PK4(p0, 8, pa1); PK4(p1, 0, pa2); PK4(p1, 8, pa3);
;     ...
; }
; template <int DQK, int SDEPTH, bool OUT_BF16, int QREG = DQK / 16, bool OUT_F16 = false> ...
;     ...
;   f32x16 pA0, pA1, pB0, pB1; float mnA, mnB, alA, alB; bf16x8 pa0, pa1, pa2, pa3; const int NT = seq / KVBLK;
;   constexpr int SE = 0, SO = SDEPTH - 1;
;   SLOAD(SE, 0); asm volatile("s_waitcnt vmcnt(0)" ::: "memory"); SWRITE(0, SE); __syncthreads();
;   QKT(pA0, pA1, K_lds); partialSM(pA0, pA1, m_reg, mnA, alA, SCALE);
;   SLOAD(SO, KVBLK); if constexpr (SDEPTH == 2) { if (2 < NT) SLOAD(SE, 2 * KVBLK); }
;   SWAIT(); SWRITE(1, SO); __syncthreads();
;   for (int j = 1; j + 1 < NT; j += 2) {
;     SBAR(); QKT(pB0, pB1, K_lds + SHM_K);
;     finishSM(pA0, pA1, alA, l_reg, pa0, pa1, pa2, pa3); SBAR();
;     SLOAD(SO, (j + SDEPTH) * KVBLK); SBAR();
;     pv_d0(o, vb0, pa0, pa1, pa2, pa3); partialSM(pB0, pB1, m_reg, mnB, alB, SCALE);
;     __syncthreads(); SWAIT(); SWRITE(0, SE);
;     RESC(alB); __syncthreads();
;     SBAR(); QKT(pA0, pA1, K_lds);
;     finishSM(pB0, pB1, alB, l_reg, pa0, pa1, pa2, pa3); SBAR();
;     if (SDEPTH == 1 || j + 3 < NT) SLOAD(SE, (j + 1 + SDEPTH) * KVBLK); SBAR();
;     pv_d0(o, vb0 + SHM_V, pa0, pa1, pa2, pa3); partialSM(pA0, pA1, m_reg, mnA, alA, SCALE);
	v_exp_f32_e32 v87, v87
	v_exp_f32_e32 v88, v88
	v_exp_f32_e32 v89, v89
	v_exp_f32_e32 v90, v90
	v_exp_f32_e32 v91, v91
	v_exp_f32_e32 v92, v92
	v_exp_f32_e32 v93, v93
	v_exp_f32_e32 v94, v94
	v_exp_f32_e32 v95, v95
	v_exp_f32_e32 v96, v96
	v_exp_f32_e32 v97, v97
	v_exp_f32_e32 v66, v66
	v_exp_f32_e32 v67, v67
	v_exp_f32_e32 v68, v68
	v_exp_f32_e32 v69, v69
	v_exp_f32_e32 v70, v70
	v_exp_f32_e32 v71, v71
	v_exp_f32_e32 v72, v72
	v_exp_f32_e32 v73, v73
	v_exp_f32_e32 v74, v74
	v_exp_f32_e32 v75, v75
	v_exp_f32_e32 v76, v76
	v_exp_f32_e32 v77, v77
	v_exp_f32_e32 v78, v78
	v_exp_f32_e32 v79, v79
	v_exp_f32_e32 v80, v80
	v_exp_f32_e32 v81, v81
	s_nop 0
	v_add_f32_e32 v252, v82, v83
	v_add_f32_e32 v252, v84, v252
	v_add_f32_e32 v252, v85, v252
	v_add_f32_e32 v252, v86, v252
	v_add_f32_e32 v252, v87, v252
	v_add_f32_e32 v252, v88, v252
	v_add_f32_e32 v252, v89, v252
	v_add_f32_e32 v252, v90, v252
	v_add_f32_e32 v252, v91, v252
	v_add_f32_e32 v252, v92, v252
	v_add_f32_e32 v252, v93, v252
	v_add_f32_e32 v252, v94, v252
	v_add_f32_e32 v252, v95, v252
	v_add_f32_e32 v252, v96, v252
	v_add_f32_e32 v252, v97, v252
	v_add_f32_e32 v252, v66, v252
	v_add_f32_e32 v252, v67, v252
	v_add_f32_e32 v252, v68, v252
	v_add_f32_e32 v252, v69, v252
	v_add_f32_e32 v252, v70, v252
	v_add_f32_e32 v252, v71, v252
	v_add_f32_e32 v252, v72, v252
	v_add_f32_e32 v252, v73, v252
	v_add_f32_e32 v252, v74, v252
	v_add_f32_e32 v252, v75, v252
	v_add_f32_e32 v252, v76, v252
	v_add_f32_e32 v252, v77, v252
	v_add_f32_e32 v252, v78, v252
	v_add_f32_e32 v252, v79, v252
	v_add_f32_e32 v252, v80, v252
	v_add_f32_e32 v252, v81, v252
	v_fma_f32 v227, v200, v166, v252
	v_cvt_pk_bf16_f32 v152, v82, v83
	v_cvt_pk_bf16_f32 v153, v84, v85
	v_cvt_pk_bf16_f32 v154, v86, v87
	v_cvt_pk_bf16_f32 v155, v88, v89
	v_cvt_pk_bf16_f32 v156, v90, v91
	v_cvt_pk_bf16_f32 v157, v92, v93
	v_cvt_pk_bf16_f32 v158, v94, v95
	v_cvt_pk_bf16_f32 v159, v96, v97
	v_cvt_pk_bf16_f32 v228, v66, v67
	v_cvt_pk_bf16_f32 v229, v68, v69
	v_cvt_pk_bf16_f32 v230, v70, v71
	v_cvt_pk_bf16_f32 v231, v72, v73
	v_cvt_pk_bf16_f32 v248, v74, v75
	v_cvt_pk_bf16_f32 v249, v76, v77
	v_cvt_pk_bf16_f32 v250, v78, v79
	v_cvt_pk_bf16_f32 v251, v80, v81
	s_and_saveexec_b64 s[10:11], s[0:1]
	ds_write_b32 v164, v200 offset:128
	s_or_b64 exec, exec, s[10:11]
	s_waitcnt lgkmcnt(0)
	v_add_u32_e32 v246, v143, v0
	ds_read_b128 v[200:203], v246 offset:224
	ds_read_b128 v[204:207], v246 offset:192
	ds_read_b128 v[208:211], v246 offset:160
	ds_read_b128 v[222:225], v246 offset:128
	s_waitcnt lgkmcnt(3)
	v_pk_mul_f32 v[14:15], v[14:15], v[200:201]
	s_waitcnt lgkmcnt(2)
	v_pk_mul_f32 v[10:11], v[10:11], v[204:205]
	s_waitcnt lgkmcnt(1)
	v_pk_mul_f32 v[6:7], v[6:7], v[208:209]
	v_pk_mul_f32 v[16:17], v[16:17], v[202:203]
	v_pk_mul_f32 v[12:13], v[12:13], v[206:207]
	v_pk_mul_f32 v[8:9], v[8:9], v[210:211]
	s_waitcnt lgkmcnt(0)
	v_pk_mul_f32 v[4:5], v[4:5], v[224:225]
	v_pk_mul_f32 v[2:3], v[2:3], v[222:223]
	v_pk_mul_f32 v[62:63], v[62:63], v[200:201]
	v_pk_mul_f32 v[58:59], v[58:59], v[204:205]
	v_pk_mul_f32 v[54:55], v[54:55], v[208:209]
	v_pk_mul_f32 v[64:65], v[64:65], v[202:203]
	v_pk_mul_f32 v[60:61], v[60:61], v[206:207]
	v_pk_mul_f32 v[56:57], v[56:57], v[210:211]
	v_pk_mul_f32 v[52:53], v[52:53], v[224:225]
	v_pk_mul_f32 v[50:51], v[50:51], v[222:223]
	v_pk_mul_f32 v[46:47], v[46:47], v[200:201]
	v_pk_mul_f32 v[42:43], v[42:43], v[204:205]
	v_pk_mul_f32 v[38:39], v[38:39], v[208:209]
	v_pk_mul_f32 v[48:49], v[48:49], v[202:203]
	v_pk_mul_f32 v[44:45], v[44:45], v[206:207]
	v_pk_mul_f32 v[40:41], v[40:41], v[210:211]
	v_pk_mul_f32 v[36:37], v[36:37], v[224:225]
	v_pk_mul_f32 v[34:35], v[34:35], v[222:223]
	v_pk_mul_f32 v[30:31], v[30:31], v[200:201]
	v_pk_mul_f32 v[26:27], v[26:27], v[204:205]
	v_pk_mul_f32 v[22:23], v[22:23], v[208:209]
	v_pk_mul_f32 v[32:33], v[32:33], v[202:203]
	v_pk_mul_f32 v[28:29], v[28:29], v[206:207]
	v_pk_mul_f32 v[24:25], v[24:25], v[210:211]
	v_pk_mul_f32 v[20:21], v[20:21], v[224:225]
	v_pk_mul_f32 v[18:19], v[18:19], v[222:223]
.LBB0_752:
	s_waitcnt lgkmcnt(0)
	s_barrier
	ds_read_b128 v[66:69], v172 offset:20480
	ds_read_b128 v[70:73], v172 offset:32768
	ds_read_b128 v[244:247], v173 offset:20480
	ds_read_b128 v[202:205], v173 offset:32768
	s_waitcnt lgkmcnt(3)
	v_mfma_f32_32x32x16_bf16 v[82:97], v[66:69], v[110:113], v[184:199]
	s_waitcnt lgkmcnt(2)
	v_mfma_f32_32x32x16_bf16 v[66:81], v[70:73], v[110:113], v[184:199]
	s_waitcnt lgkmcnt(1)
	v_mfma_f32_32x32x16_bf16 v[82:97], v[244:247], v[106:109], v[82:97]
	s_waitcnt lgkmcnt(0)
	v_mfma_f32_32x32x16_bf16 v[66:81], v[202:205], v[106:109], v[66:81]
	ds_read_b128 v[244:247], v174 offset:20480
	ds_read_b128 v[202:205], v174 offset:32768
	s_waitcnt lgkmcnt(1)
	v_mfma_f32_32x32x16_bf16 v[82:97], v[244:247], v[102:105], v[82:97]
	s_waitcnt lgkmcnt(0)
	v_mfma_f32_32x32x16_bf16 v[66:81], v[202:205], v[102:105], v[66:81]
	ds_read_b128 v[244:247], v175 offset:20480
	ds_read_b128 v[202:205], v175 offset:32768
	s_waitcnt lgkmcnt(1)
	v_mfma_f32_32x32x16_bf16 v[82:97], v[244:247], v[98:101], v[82:97]
	s_waitcnt lgkmcnt(0)
	v_mfma_f32_32x32x16_bf16 v[66:81], v[202:205], v[98:101], v[66:81]
	ds_read_b128 v[244:247], v176 offset:20480
	ds_read_b128 v[202:205], v176 offset:32768
	ds_read_b128 v[206:209], v162
	s_waitcnt lgkmcnt(0)
	v_mfma_f32_32x32x16_bf16 v[82:97], v[244:247], v[206:209], v[82:97]
	v_mfma_f32_32x32x16_bf16 v[66:81], v[202:205], v[206:209], v[66:81]
	ds_read_b128 v[244:247], v177 offset:20480
	ds_read_b128 v[202:205], v177 offset:32768
	ds_read_b128 v[206:209], v162 offset:1024
	s_waitcnt lgkmcnt(0)
; #define LAS __attribute__((address_space(3)))
; DI void finishSM(f32x16& p0, f32x16& p1, float alpha, float& l_reg, bf16x8& pa0, bf16x8& pa1, bf16x8& pa2, bf16x8& pa3) {
; #pragma unroll
;   for (int r = 0; r < 16; ++r) p1[r] = __builtin_amdgcn_exp2f(p1[r]);
;   float ps = 0;
; #pragma unroll
;   for (int r = 0; r < 16; ++r) ps += p0[r];
; #pragma unroll
;   for (int r = 0; r < 16; ++r) ps += p1[r];
;   { auto rr = __builtin_amdgcn_permlane32_swap(__float_as_uint(ps), __float_as_uint(ps), false, false);
;     ps = __uint_as_float(rr[0]) + __uint_as_float(rr[1]); }
;   l_reg = l_reg * alpha + ps;
;     ...
;   PK4(p0, 0, pa0); PK4(p0, 8, pa1); PK4(p1, 0, pa2); PK4(p1, 8, pa3);
;     ...
; }
; template <int DQK> DI void qkt(f32x16& p0, f32x16& p1, const LAS char* Ks, const bf16x8* qr, int r32, int hi) {
;   p0 = f32x16{}; p1 = f32x16{};
; #pragma unroll
;   for (int d0 = 0; d0 < DQK / 16; ++d0) { const int cb = (d0 * 16 + hi * 8) * 2;
;     const bf16x8 b0 = *(const LAS bf16x8*)(Ks + kswz<DQK>(r32, cb));
;     const bf16x8 b1 = *(const LAS bf16x8*)(Ks + kswz<DQK>(32 + r32, cb));
;     p0 = __builtin_amdgcn_mfma_f32_32x32x16_bf16(b0, qr[d0], p0, 0, 0, 0);
;     p1 = __builtin_amdgcn_mfma_f32_32x32x16_bf16(b1, qr[d0], p1, 0, 0, 0); }
; }
; DI int v_st(int k, int c) { const int kk = (k & ~0xC) | ((k & 4) << 1) | ((k & 8) >> 1); return ((kk >> 3) * 4 + (c >> 5)) * 512 + ((kk & 7) * 32 + (c & 31)) * 2; }
; DI int v_rd_base(int lane) { return ((lane & 3) << 3) | (((lane >> 2) & 3) << 6) | (((lane >> 4) & 1) << 5) | (((lane >> 5) & 1) << 8); }
; template <int OFF> DI s16x4 tr_read(int vb) { s16x4 r; asm volatile("ds_read_b64_tr_b16 %0, %1 offset:%2" : "=&v"(r) : "v"(vb), "i"(OFF) : "memory"); return r; }
; template <int D0> DI void pv_one(f32x16& od, int vb, bf16x8 pa0, bf16x8 pa1, bf16x8 pa2, bf16x8 pa3) {
;   const s16x4 l0 = tr_read<v_rd_off(D0, 0, 0)>(vb), h0 = tr_read<v_rd_off(D0, 0, 1)>(vb), l1 = tr_read<v_rd_off(D0, 1, 0)>(vb), h1 = tr_read<v_rd_off(D0, 1, 1)>(vb);
;   const s16x4 l2 = tr_read<v_rd_off(D0, 2, 0)>(vb), h2 = tr_read<v_rd_off(D0, 2, 1)>(vb), l3 = tr_read<v_rd_off(D0, 3, 0)>(vb), h3 = tr_read<v_rd_off(D0, 3, 1)>(vb);
;   asm volatile("s_waitcnt lgkmcnt(0)" ::: "memory"); SBAR();
;     ...
;   od = __builtin_amdgcn_mfma_f32_32x32x16_bf16(pa0, PK(l0, h0), od, 0, 0, 0);
;   od = __builtin_amdgcn_mfma_f32_32x32x16_bf16(pa1, PK(l1, h1), od, 0, 0, 0);
	v_mfma_f32_32x32x16_bf16 v[82:97], v[244:247], v[206:209], v[82:97]
	v_mfma_f32_32x32x16_bf16 v[66:81], v[202:205], v[206:209], v[66:81]
	ds_read_b128 v[244:247], v178 offset:20480
	ds_read_b128 v[202:205], v178 offset:32768
	ds_read_b128 v[206:209], v162 offset:2048
	s_waitcnt lgkmcnt(0)
	v_mfma_f32_32x32x16_bf16 v[82:97], v[244:247], v[206:209], v[82:97]
	v_mfma_f32_32x32x16_bf16 v[66:81], v[202:205], v[206:209], v[66:81]
	ds_read_b128 v[244:247], v179 offset:20480
	ds_read_b128 v[202:205], v179 offset:32768
	ds_read_b128 v[206:209], v162 offset:3072
	s_waitcnt lgkmcnt(0)
	v_mfma_f32_32x32x16_bf16 v[82:97], v[244:247], v[206:209], v[82:97]
	v_mfma_f32_32x32x16_bf16 v[66:81], v[202:205], v[206:209], v[66:81]
	ds_read_b128 v[244:247], v180 offset:20480
	ds_read_b128 v[202:205], v180 offset:32768
	ds_read_b128 v[206:209], v162 offset:4096
	s_waitcnt lgkmcnt(0)
	v_mfma_f32_32x32x16_bf16 v[82:97], v[244:247], v[206:209], v[82:97]
	v_mfma_f32_32x32x16_bf16 v[66:81], v[202:205], v[206:209], v[66:81]
	ds_read_b128 v[244:247], v181 offset:20480
	ds_read_b128 v[202:205], v181 offset:32768
	ds_read_b128 v[206:209], v162 offset:5120
	s_waitcnt lgkmcnt(0)
	v_mfma_f32_32x32x16_bf16 v[82:97], v[244:247], v[206:209], v[82:97]
	v_mfma_f32_32x32x16_bf16 v[66:81], v[202:205], v[206:209], v[66:81]
	ds_read_b128 v[244:247], v182 offset:20480
	ds_read_b128 v[202:205], v182 offset:32768
	ds_read_b128 v[206:209], v162 offset:6144
	s_waitcnt lgkmcnt(0)
	v_mfma_f32_32x32x16_bf16 v[82:97], v[244:247], v[206:209], v[82:97]
	v_mfma_f32_32x32x16_bf16 v[66:81], v[202:205], v[206:209], v[66:81]
	ds_read_b128 v[244:247], v183 offset:20480
	ds_read_b128 v[202:205], v183 offset:32768
	ds_read_b128 v[206:209], v162 offset:7168
	s_waitcnt lgkmcnt(0)
	v_mfma_f32_32x32x16_bf16 v[82:97], v[244:247], v[206:209], v[82:97]
	v_mfma_f32_32x32x16_bf16 v[66:81], v[202:205], v[206:209], v[66:81]
	ds_read_b64_tr_b16 v[200:201], v165 offset:0x0
	ds_read_b64_tr_b16 v[202:203], v165 offset:0x100
	ds_read_b64_tr_b16 v[204:205], v165 offset:0x1000
	ds_read_b64_tr_b16 v[206:207], v165 offset:0x1100
	ds_read_b64_tr_b16 v[208:209], v165 offset:0x2000
	ds_read_b64_tr_b16 v[210:211], v165 offset:0x2100
	ds_read_b64_tr_b16 v[222:223], v165 offset:0x3000
	ds_read_b64_tr_b16 v[224:225], v165 offset:0x3100
	s_waitcnt lgkmcnt(0)
	v_mfma_f32_32x32x16_bf16 v[2:17], v[152:155], v[200:203], v[2:17]
	ds_read_b64_tr_b16 v[200:201], v165 offset:0x200
	ds_read_b64_tr_b16 v[202:203], v165 offset:0x300
	v_exp_f32_e32 v82, v82
	v_exp_f32_e32 v83, v83
	v_exp_f32_e32 v84, v84
	v_exp_f32_e32 v85, v85
	v_exp_f32_e32 v86, v86
	v_mfma_f32_32x32x16_bf16 v[2:17], v[156:159], v[204:207], v[2:17]
	ds_read_b64_tr_b16 v[204:205], v165 offset:0x1200
	ds_read_b64_tr_b16 v[206:207], v165 offset:0x1300
	v_add_f32_e32 v252, v82, v83
	v_exp_f32_e32 v87, v87
	v_add_f32_e32 v252, v84, v252
	v_exp_f32_e32 v88, v88
	v_add_f32_e32 v252, v85, v252
	v_mfma_f32_32x32x16_bf16 v[2:17], v[228:231], v[208:211], v[2:17]
	ds_read_b64_tr_b16 v[208:209], v165 offset:0x2200
	ds_read_b64_tr_b16 v[210:211], v165 offset:0x2300
	v_cvt_pk_bf16_f32 v134, v82, v83
	v_exp_f32_e32 v89, v89
	v_add_f32_e32 v252, v86, v252
	v_exp_f32_e32 v90, v90
	v_add_f32_e32 v252, v87, v252
	v_mfma_f32_32x32x16_bf16 v[2:17], v[248:251], v[222:225], v[2:17]
	ds_read_b64_tr_b16 v[222:223], v165 offset:0x3200
	ds_read_b64_tr_b16 v[224:225], v165 offset:0x3300
	v_cvt_pk_bf16_f32 v135, v84, v85
	v_exp_f32_e32 v91, v91
	v_add_f32_e32 v252, v88, v252
	v_exp_f32_e32 v92, v92
	v_add_f32_e32 v252, v89, v252
	s_waitcnt lgkmcnt(0)
	v_mfma_f32_32x32x16_bf16 v[50:65], v[152:155], v[200:203], v[50:65]
	ds_read_b64_tr_b16 v[200:201], v165 offset:0x400
	ds_read_b64_tr_b16 v[202:203], v165 offset:0x500
	v_cvt_pk_bf16_f32 v136, v86, v87
	v_exp_f32_e32 v93, v93
	v_add_f32_e32 v252, v90, v252
	v_exp_f32_e32 v94, v94
	v_add_f32_e32 v252, v91, v252
	v_mfma_f32_32x32x16_bf16 v[50:65], v[156:159], v[204:207], v[50:65]
	ds_read_b64_tr_b16 v[204:205], v165 offset:0x1400
	ds_read_b64_tr_b16 v[206:207], v165 offset:0x1500
	v_cvt_pk_bf16_f32 v137, v88, v89
	v_exp_f32_e32 v95, v95
	v_add_f32_e32 v252, v92, v252
	v_exp_f32_e32 v96, v96
	v_add_f32_e32 v252, v93, v252
	v_mfma_f32_32x32x16_bf16 v[50:65], v[228:231], v[208:211], v[50:65]
	ds_read_b64_tr_b16 v[208:209], v165 offset:0x2400
	ds_read_b64_tr_b16 v[210:211], v165 offset:0x2500
	v_cvt_pk_bf16_f32 v138, v90, v91
	v_exp_f32_e32 v97, v97
	v_add_f32_e32 v252, v94, v252
	v_exp_f32_e32 v66, v66
	v_add_f32_e32 v252, v95, v252
	v_mfma_f32_32x32x16_bf16 v[50:65], v[248:251], v[222:225], v[50:65]
	ds_read_b64_tr_b16 v[222:223], v165 offset:0x3400
	ds_read_b64_tr_b16 v[224:225], v165 offset:0x3500
	v_cvt_pk_bf16_f32 v139, v92, v93
	v_exp_f32_e32 v67, v67
	v_add_f32_e32 v252, v96, v252
	v_exp_f32_e32 v68, v68
	v_add_f32_e32 v252, v97, v252
	s_waitcnt lgkmcnt(0)
	v_mfma_f32_32x32x16_bf16 v[34:49], v[152:155], v[200:203], v[34:49]
	ds_read_b64_tr_b16 v[200:201], v165 offset:0x600
	ds_read_b64_tr_b16 v[202:203], v165 offset:0x700
	v_cvt_pk_bf16_f32 v140, v94, v95
	v_exp_f32_e32 v69, v69
	v_add_f32_e32 v252, v66, v252
	v_exp_f32_e32 v70, v70
	v_add_f32_e32 v252, v67, v252
	v_cvt_pk_bf16_f32 v141, v96, v97
	v_mfma_f32_32x32x16_bf16 v[34:49], v[156:159], v[204:207], v[34:49]
	ds_read_b64_tr_b16 v[204:205], v165 offset:0x1600
	ds_read_b64_tr_b16 v[206:207], v165 offset:0x1700
	v_exp_f32_e32 v71, v71
	v_add_f32_e32 v252, v68, v252
	v_exp_f32_e32 v72, v72
	v_add_f32_e32 v252, v69, v252
	v_cvt_pk_bf16_f32 v214, v66, v67
	v_mfma_f32_32x32x16_bf16 v[34:49], v[228:231], v[208:211], v[34:49]
	ds_read_b64_tr_b16 v[208:209], v165 offset:0x2600
	ds_read_b64_tr_b16 v[210:211], v165 offset:0x2700
	v_exp_f32_e32 v73, v73
	v_add_f32_e32 v252, v70, v252
	v_exp_f32_e32 v74, v74
	v_add_f32_e32 v252, v71, v252
	v_cvt_pk_bf16_f32 v215, v68, v69
	v_mfma_f32_32x32x16_bf16 v[34:49], v[248:251], v[222:225], v[34:49]
	ds_read_b64_tr_b16 v[222:223], v165 offset:0x3600
	ds_read_b64_tr_b16 v[224:225], v165 offset:0x3700
	v_exp_f32_e32 v75, v75
	v_add_f32_e32 v252, v72, v252
	v_exp_f32_e32 v76, v76
	v_add_f32_e32 v252, v73, v252
	v_cvt_pk_bf16_f32 v216, v70, v71
	s_waitcnt lgkmcnt(0)
	v_mfma_f32_32x32x16_bf16 v[18:33], v[152:155], v[200:203], v[18:33]
	v_exp_f32_e32 v77, v77
	v_add_f32_e32 v252, v74, v252
	v_exp_f32_e32 v78, v78
	v_add_f32_e32 v252, v75, v252
	v_cvt_pk_bf16_f32 v217, v72, v73
	v_mfma_f32_32x32x16_bf16 v[18:33], v[156:159], v[204:207], v[18:33]
	v_exp_f32_e32 v79, v79
	v_add_f32_e32 v252, v76, v252
	v_exp_f32_e32 v80, v80
	v_add_f32_e32 v252, v77, v252
	v_cvt_pk_bf16_f32 v218, v74, v75
	v_mfma_f32_32x32x16_bf16 v[18:33], v[228:231], v[208:211], v[18:33]
	v_exp_f32_e32 v81, v81
	v_add_f32_e32 v252, v78, v252
	v_add_f32_e32 v252, v79, v252
	v_cvt_pk_bf16_f32 v219, v76, v77
	v_add_f32_e32 v252, v80, v252
	v_mfma_f32_32x32x16_bf16 v[18:33], v[248:251], v[222:225], v[18:33]
	v_add_f32_e32 v252, v81, v252
	v_cvt_pk_bf16_f32 v220, v78, v79
	v_cvt_pk_bf16_f32 v221, v80, v81
	v_cmp_nge_f32_e32 vcc, 0x453a4f54, v252
	v_add_f32_e32 v166, v227, v252
	s_barrier
; #define SBAR() __builtin_amdgcn_sched_barrier(0)
; #define SLOAD(i, k0) do { sr_[i].vs0 = *reinterpret_cast<const bf16x8*>(&Vh[(long)((k0) + sr) * DV + sc]); sr_[i].vs1 = *reinterpret_cast<const bf16x8*>(&Vh[(long)((k0) + 32 + sr) * DV + sc]); \
;     _Pragma("unroll") for (int _c = 0; _c < NKC; ++_c) sr_[i].ks[_c] = *reinterpret_cast<const bf16x8*>(&Kh[(long)((k0) + krow[_c]) * DQK + kcol[_c]]); } while (0)
; #define SWRITE(b, i) do { *(LAS bf16x8*)(V_lds + (b) * SHM_V + vst0) = sr_[i].vs0; *(LAS bf16x8*)(V_lds + (b) * SHM_V + vst1) = sr_[i].vs1; \
;     _Pragma("unroll") for (int _c = 0; _c < NKC; ++_c) *(LAS bf16x8*)(K_lds + (b) * SHM_K + kswz<DQK>(krow[_c], kcol[_c] * 2)) = sr_[i].ks[_c]; } while (0)
; #define SWAIT() do { if constexpr (SDEPTH == 2) { if constexpr (NKC == 1) asm volatile("s_waitcnt vmcnt(3)" ::: "memory"); else if constexpr (NKC == 2) asm volatile("s_waitcnt vmcnt(4)" ::: "memory"); else asm volatile("s_waitcnt vmcnt(5)" ::: "memory"); } \
;     else asm volatile("s_waitcnt vmcnt(0)" ::: "memory"); } while (0)
; #define RESC(a) do { if (__any((a) < 1.f)) { if (hi == 0) al_l[r32] = (a); asm volatile("s_waitcnt lgkmcnt(0)" ::: "memory"); \
;     _Pragma("unroll") for (int d = 0; d < 4; ++d) _Pragma("unroll") for (int r = 0; r < 16; ++r) o[d][r] *= al_l[crow(r, hi)]; } } while (0)
; DI void partialSM(f32x16& p0, f32x16& p1, float& m_reg, float& mn, float& alpha, const float SCALE) {
;   const float C = SCALE * 1.4426950408889634f;
;   float pmax = p0[0];
; #pragma unroll
;   for (int r = 1; r < 16; ++r) pmax = fmaxf(pmax, p0[r]);
; #pragma unroll
;   for (int r = 0; r < 16; ++r) pmax = fmaxf(pmax, p1[r]);
;   { auto rr = __builtin_amdgcn_permlane32_swap(__float_as_uint(pmax), __float_as_uint(pmax), false, false);
;     pmax = fmaxf(__uint_as_float(rr[0]), __uint_as_float(rr[1])); }
;   if (__builtin_expect(__all(pmax - m_reg <= THR / SCALE), 1)) { mn = m_reg; alpha = 1.f; }
;   else { mn = fmaxf(m_reg, pmax); alpha = __builtin_amdgcn_exp2f((m_reg - mn) * C); m_reg = mn; }
; template <int DQK, int SDEPTH, bool OUT_BF16, int QREG = DQK / 16, bool OUT_F16 = false> ...
;     ...
;     if (SDEPTH == 1 || j + 3 < NT) SLOAD(SE, (j + 1 + SDEPTH) * KVBLK); SBAR();
;     pv_d0(o, vb0 + SHM_V, pa0, pa1, pa2, pa3); partialSM(pA0, pA1, m_reg, mnA, alA, SCALE);
;     __syncthreads(); SWAIT(); SWRITE(1, SO);
;     RESC(alA); __syncthreads();
	s_waitcnt vmcnt(0)
	ds_write_b128 v167, v[114:117] offset:16384
	ds_write_b128 v168, v[118:121] offset:16384
	ds_write_b128 v169, v[122:125] offset:57344
	ds_write_b128 v170, v[126:129] offset:57344
	ds_write_b128 v171, v[130:133] offset:57344
	v_mov_b32_e32 v247, 1.0
	v_lshl_add_u64 v[144:145], v[144:145], 0, s[52:53]
	v_lshl_add_u64 v[146:147], v[146:147], 0, s[52:53]
	v_lshl_add_u64 v[148:149], v[148:149], 0, s[52:53]
	v_lshl_add_u64 v[150:151], v[150:151], 0, s[54:55]
	s_add_i32 s41, s41, 2
	s_cmp_ge_u32 s41, s40
	s_cbranch_scc1 .Lmla_skip_loads
	global_load_dwordx4 v[114:117], v150, s[80:81]
	global_load_dwordx4 v[118:121], v150, s[82:83]
	global_load_dwordx4 v[122:125], v148, s[84:85]
	global_load_dwordx4 v[126:129], v146, s[84:85]
	global_load_dwordx4 v[130:133], v144, s[84:85]
.Lmla_skip_loads:
	s_cbranch_vccz .LBB0_756
	ds_read_b128 v[66:69], v172 offset:20480
	ds_read_b128 v[70:73], v172 offset:32768
	ds_read_b128 v[244:247], v173 offset:20480
	ds_read_b128 v[202:205], v173 offset:32768
	s_waitcnt lgkmcnt(3)
	v_mfma_f32_32x32x16_bf16 v[82:97], v[66:69], v[110:113], 0
	s_waitcnt lgkmcnt(2)
	v_mfma_f32_32x32x16_bf16 v[66:81], v[70:73], v[110:113], 0
	s_waitcnt lgkmcnt(1)
	v_mfma_f32_32x32x16_bf16 v[82:97], v[244:247], v[106:109], v[82:97]
	s_waitcnt lgkmcnt(0)
	v_mfma_f32_32x32x16_bf16 v[66:81], v[202:205], v[106:109], v[66:81]
	ds_read_b128 v[244:247], v174 offset:20480
	ds_read_b128 v[202:205], v174 offset:32768
	s_waitcnt lgkmcnt(1)
	v_mfma_f32_32x32x16_bf16 v[82:97], v[244:247], v[102:105], v[82:97]
	s_waitcnt lgkmcnt(0)
	v_mfma_f32_32x32x16_bf16 v[66:81], v[202:205], v[102:105], v[66:81]
	ds_read_b128 v[244:247], v175 offset:20480
	ds_read_b128 v[202:205], v175 offset:32768
	s_waitcnt lgkmcnt(1)
	v_mfma_f32_32x32x16_bf16 v[82:97], v[244:247], v[98:101], v[82:97]
	s_waitcnt lgkmcnt(0)
	v_mfma_f32_32x32x16_bf16 v[66:81], v[202:205], v[98:101], v[66:81]
	ds_read_b128 v[244:247], v176 offset:20480
	ds_read_b128 v[202:205], v176 offset:32768
	ds_read_b128 v[206:209], v162
	s_waitcnt lgkmcnt(0)
	v_mfma_f32_32x32x16_bf16 v[82:97], v[244:247], v[206:209], v[82:97]
	v_mfma_f32_32x32x16_bf16 v[66:81], v[202:205], v[206:209], v[66:81]
	ds_read_b128 v[244:247], v177 offset:20480
	ds_read_b128 v[202:205], v177 offset:32768
	ds_read_b128 v[206:209], v162 offset:1024
	s_waitcnt lgkmcnt(0)
	v_mfma_f32_32x32x16_bf16 v[82:97], v[244:247], v[206:209], v[82:97]
	v_mfma_f32_32x32x16_bf16 v[66:81], v[202:205], v[206:209], v[66:81]
	ds_read_b128 v[244:247], v178 offset:20480
	ds_read_b128 v[202:205], v178 offset:32768
	ds_read_b128 v[206:209], v162 offset:2048
	s_waitcnt lgkmcnt(0)
	v_mfma_f32_32x32x16_bf16 v[82:97], v[244:247], v[206:209], v[82:97]
	v_mfma_f32_32x32x16_bf16 v[66:81], v[202:205], v[206:209], v[66:81]
	ds_read_b128 v[244:247], v179 offset:20480
	ds_read_b128 v[202:205], v179 offset:32768
	ds_read_b128 v[206:209], v162 offset:3072
	s_waitcnt lgkmcnt(0)
	v_mfma_f32_32x32x16_bf16 v[82:97], v[244:247], v[206:209], v[82:97]
	v_mfma_f32_32x32x16_bf16 v[66:81], v[202:205], v[206:209], v[66:81]
	ds_read_b128 v[244:247], v180 offset:20480
	ds_read_b128 v[202:205], v180 offset:32768
	ds_read_b128 v[206:209], v162 offset:4096
	s_waitcnt lgkmcnt(0)
	v_mfma_f32_32x32x16_bf16 v[82:97], v[244:247], v[206:209], v[82:97]
	v_mfma_f32_32x32x16_bf16 v[66:81], v[202:205], v[206:209], v[66:81]
	ds_read_b128 v[244:247], v181 offset:20480
	ds_read_b128 v[202:205], v181 offset:32768
	ds_read_b128 v[206:209], v162 offset:5120
	s_waitcnt lgkmcnt(0)
	v_mfma_f32_32x32x16_bf16 v[82:97], v[244:247], v[206:209], v[82:97]
	v_mfma_f32_32x32x16_bf16 v[66:81], v[202:205], v[206:209], v[66:81]
	ds_read_b128 v[244:247], v182 offset:20480
	ds_read_b128 v[202:205], v182 offset:32768
	ds_read_b128 v[206:209], v162 offset:6144
	s_waitcnt lgkmcnt(0)
	v_mfma_f32_32x32x16_bf16 v[82:97], v[244:247], v[206:209], v[82:97]
	v_mfma_f32_32x32x16_bf16 v[66:81], v[202:205], v[206:209], v[66:81]
	ds_read_b128 v[244:247], v183 offset:20480
	ds_read_b128 v[202:205], v183 offset:32768
	ds_read_b128 v[206:209], v162 offset:7168
	s_waitcnt lgkmcnt(0)
	v_mfma_f32_32x32x16_bf16 v[82:97], v[244:247], v[206:209], v[82:97]
	v_mfma_f32_32x32x16_bf16 v[66:81], v[202:205], v[206:209], v[66:81]
	s_nop 7
	s_nop 7
	v_max3_f32 v244, v82, v83, v84
	v_max3_f32 v245, v85, v86, v87
	v_max3_f32 v244, v244, v88, v89
	v_max3_f32 v245, v245, v90, v91
	v_max3_f32 v244, v244, v92, v93
	v_max3_f32 v245, v245, v94, v95
	v_max3_f32 v244, v244, v96, v97
	v_max3_f32 v245, v245, v66, v67
	v_max3_f32 v244, v244, v68, v69
	v_max3_f32 v245, v245, v70, v71
	v_max3_f32 v244, v244, v72, v73
	v_max3_f32 v245, v245, v74, v75
	v_max3_f32 v244, v244, v76, v77
	v_max3_f32 v245, v245, v78, v79
	v_max3_f32 v244, v244, v80, v81
	v_max_f32_e32 v244, v244, v245
	v_mov_b32_e32 v245, v244
	s_nop 1
	v_permlane32_swap_b32_e32 v244, v245
	v_max_f32_e32 v244, v244, v245
	v_max_f32_e64 v244, -v226, v244
	v_sub_f32_e64 v245, -v226, v244
	v_exp_f32_e32 v247, v245
	v_mul_f32_e32 v226, 0xbf800000, v244
	v_mov_b32_e32 v184, v226
	v_mov_b32_e32 v185, v226
	v_mov_b32_e32 v186, v226
	v_mov_b32_e32 v187, v226
	v_mov_b32_e32 v188, v226
	v_mov_b32_e32 v189, v226
	v_mov_b32_e32 v190, v226
	v_mov_b32_e32 v191, v226
	v_mov_b32_e32 v192, v226
	v_mov_b32_e32 v193, v226
	v_mov_b32_e32 v194, v226
	v_mov_b32_e32 v195, v226
	v_mov_b32_e32 v196, v226
	v_mov_b32_e32 v197, v226
	v_mov_b32_e32 v198, v226
	v_mov_b32_e32 v199, v226
	v_add_f32_e32 v82, v226, v82
	v_add_f32_e32 v83, v226, v83
	v_add_f32_e32 v84, v226, v84
	v_add_f32_e32 v85, v226, v85
	v_add_f32_e32 v86, v226, v86
	v_add_f32_e32 v87, v226, v87
	v_add_f32_e32 v88, v226, v88
	v_add_f32_e32 v89, v226, v89
; #define SBAR() __builtin_amdgcn_sched_barrier(0)
; DI void finishSM(f32x16& p0, f32x16& p1, float alpha, float& l_reg, bf16x8& pa0, bf16x8& pa1, bf16x8& pa2, bf16x8& pa3) {
; #pragma unroll
;   for (int r = 0; r < 16; ++r) p1[r] = __builtin_amdgcn_exp2f(p1[r]);
;   float ps = 0;
; #pragma unroll
;   for (int r = 0; r < 16; ++r) ps += p0[r];
; #pragma unroll
;   for (int r = 0; r < 16; ++r) ps += p1[r];
;   { auto rr = __builtin_amdgcn_permlane32_swap(__float_as_uint(ps), __float_as_uint(ps), false, false);
;     ps = __uint_as_float(rr[0]) + __uint_as_float(rr[1]); }
;   l_reg = l_reg * alpha + ps;
;     ...
;   PK4(p0, 0, pa0); PK4(p0, 8, pa1); PK4(p1, 0, pa2); PK4(p1, 8, pa3);
;     ...
; }
; template <int DQK, int SDEPTH, bool OUT_BF16, int QREG = DQK / 16, bool OUT_F16 = false> ...
;     ...
;   f32x16 pA0, pA1, pB0, pB1; float mnA, mnB, alA, alB; bf16x8 pa0, pa1, pa2, pa3; const int NT = seq / KVBLK;
;   constexpr int SE = 0, SO = SDEPTH - 1;
;   SLOAD(SE, 0); asm volatile("s_waitcnt vmcnt(0)" ::: "memory"); SWRITE(0, SE); __syncthreads();
;   QKT(pA0, pA1, K_lds); partialSM(pA0, pA1, m_reg, mnA, alA, SCALE);
;   SLOAD(SO, KVBLK); if constexpr (SDEPTH == 2) { if (2 < NT) SLOAD(SE, 2 * KVBLK); }
;   SWAIT(); SWRITE(1, SO); __syncthreads();
;   for (int j = 1; j + 1 < NT; j += 2) {
;     SBAR(); QKT(pB0, pB1, K_lds + SHM_K);
;     finishSM(pA0, pA1, alA, l_reg, pa0, pa1, pa2, pa3); SBAR();
;     SLOAD(SO, (j + SDEPTH) * KVBLK); SBAR();
;     pv_d0(o, vb0, pa0, pa1, pa2, pa3); partialSM(pB0, pB1, m_reg, mnB, alB, SCALE);
;     __syncthreads(); SWAIT(); SWRITE(0, SE);
;     RESC(alB); __syncthreads();
;     SBAR(); QKT(pA0, pA1, K_lds);
;     finishSM(pB0, pB1, alB, l_reg, pa0, pa1, pa2, pa3); SBAR();
;     if (SDEPTH == 1 || j + 3 < NT) SLOAD(SE, (j + 1 + SDEPTH) * KVBLK); SBAR();
;     pv_d0(o, vb0 + SHM_V, pa0, pa1, pa2, pa3); partialSM(pA0, pA1, m_reg, mnA, alA, SCALE);
;     __syncthreads(); SWAIT(); SWRITE(1, SO);
;     RESC(alA); __syncthreads();
;   }
;   SBAR(); QKT(pB0, pB1, K_lds + SHM_K);
;   finishSM(pA0, pA1, alA, l_reg, pa0, pa1, pa2, pa3); SBAR();
;   pv_d0(o, vb0, pa0, pa1, pa2, pa3); partialSM(pB0, pB1, m_reg, mnB, alB, SCALE);
;   __syncthreads(); RESC(alB);
	v_add_f32_e32 v90, v226, v90
	v_add_f32_e32 v91, v226, v91
	v_add_f32_e32 v92, v226, v92
	v_add_f32_e32 v93, v226, v93
	v_add_f32_e32 v94, v226, v94
	v_add_f32_e32 v95, v226, v95
	v_add_f32_e32 v96, v226, v96
	v_add_f32_e32 v97, v226, v97
	v_add_f32_e32 v66, v226, v66
	v_add_f32_e32 v67, v226, v67
	v_add_f32_e32 v68, v226, v68
	v_add_f32_e32 v69, v226, v69
	v_add_f32_e32 v70, v226, v70
	v_add_f32_e32 v71, v226, v71
	v_add_f32_e32 v72, v226, v72
	v_add_f32_e32 v73, v226, v73
	v_add_f32_e32 v74, v226, v74
	v_add_f32_e32 v75, v226, v75
	v_add_f32_e32 v76, v226, v76
	v_add_f32_e32 v77, v226, v77
	v_add_f32_e32 v78, v226, v78
	v_add_f32_e32 v79, v226, v79
	v_add_f32_e32 v80, v226, v80
	v_add_f32_e32 v81, v226, v81
	v_exp_f32_e32 v82, v82
	v_exp_f32_e32 v83, v83
	v_exp_f32_e32 v84, v84
	v_exp_f32_e32 v85, v85
	v_exp_f32_e32 v86, v86
	v_exp_f32_e32 v87, v87
	v_exp_f32_e32 v88, v88
	v_exp_f32_e32 v89, v89
	v_exp_f32_e32 v90, v90
	v_exp_f32_e32 v91, v91
	v_exp_f32_e32 v92, v92
	v_exp_f32_e32 v93, v93
	v_exp_f32_e32 v94, v94
	v_exp_f32_e32 v95, v95
	v_exp_f32_e32 v96, v96
	v_exp_f32_e32 v97, v97
	v_exp_f32_e32 v66, v66
	v_exp_f32_e32 v67, v67
	v_exp_f32_e32 v68, v68
	v_exp_f32_e32 v69, v69
	v_exp_f32_e32 v70, v70
	v_exp_f32_e32 v71, v71
	v_exp_f32_e32 v72, v72
	v_exp_f32_e32 v73, v73
	v_exp_f32_e32 v74, v74
	v_exp_f32_e32 v75, v75
	v_exp_f32_e32 v76, v76
	v_exp_f32_e32 v77, v77
	v_exp_f32_e32 v78, v78
	v_exp_f32_e32 v79, v79
	v_exp_f32_e32 v80, v80
	v_exp_f32_e32 v81, v81
	s_nop 0
	v_add_f32_e32 v252, v82, v83
	v_add_f32_e32 v252, v84, v252
	v_add_f32_e32 v252, v85, v252
	v_add_f32_e32 v252, v86, v252
	v_add_f32_e32 v252, v87, v252
	v_add_f32_e32 v252, v88, v252
	v_add_f32_e32 v252, v89, v252
	v_add_f32_e32 v252, v90, v252
	v_add_f32_e32 v252, v91, v252
	v_add_f32_e32 v252, v92, v252
	v_add_f32_e32 v252, v93, v252
	v_add_f32_e32 v252, v94, v252
	v_add_f32_e32 v252, v95, v252
	v_add_f32_e32 v252, v96, v252
	v_add_f32_e32 v252, v97, v252
	v_add_f32_e32 v252, v66, v252
	v_add_f32_e32 v252, v67, v252
	v_add_f32_e32 v252, v68, v252
	v_add_f32_e32 v252, v69, v252
	v_add_f32_e32 v252, v70, v252
	v_add_f32_e32 v252, v71, v252
	v_add_f32_e32 v252, v72, v252
	v_add_f32_e32 v252, v73, v252
	v_add_f32_e32 v252, v74, v252
	v_add_f32_e32 v252, v75, v252
	v_add_f32_e32 v252, v76, v252
	v_add_f32_e32 v252, v77, v252
	v_add_f32_e32 v252, v78, v252
	v_add_f32_e32 v252, v79, v252
	v_add_f32_e32 v252, v80, v252
	v_add_f32_e32 v252, v81, v252
	v_fma_f32 v166, v247, v227, v252
	v_cvt_pk_bf16_f32 v134, v82, v83
	v_cvt_pk_bf16_f32 v135, v84, v85
	v_cvt_pk_bf16_f32 v136, v86, v87
	v_cvt_pk_bf16_f32 v137, v88, v89
	v_cvt_pk_bf16_f32 v138, v90, v91
	v_cvt_pk_bf16_f32 v139, v92, v93
	v_cvt_pk_bf16_f32 v140, v94, v95
	v_cvt_pk_bf16_f32 v141, v96, v97
	v_cvt_pk_bf16_f32 v214, v66, v67
	v_cvt_pk_bf16_f32 v215, v68, v69
	v_cvt_pk_bf16_f32 v216, v70, v71
	v_cvt_pk_bf16_f32 v217, v72, v73
	v_cvt_pk_bf16_f32 v218, v74, v75
	v_cvt_pk_bf16_f32 v219, v76, v77
	v_cvt_pk_bf16_f32 v220, v78, v79
	v_cvt_pk_bf16_f32 v221, v80, v81
	s_and_saveexec_b64 s[10:11], s[0:1]
	ds_write_b32 v164, v247 offset:128
	s_or_b64 exec, exec, s[10:11]
	s_waitcnt lgkmcnt(0)
	v_add_u32_e32 v246, v143, v0
	ds_read_b128 v[200:203], v246 offset:224
	ds_read_b128 v[204:207], v246 offset:192
	ds_read_b128 v[208:211], v246 offset:160
	ds_read_b128 v[222:225], v246 offset:128
	s_waitcnt lgkmcnt(3)
	v_pk_mul_f32 v[14:15], v[14:15], v[200:201]
	s_waitcnt lgkmcnt(2)
	v_pk_mul_f32 v[10:11], v[10:11], v[204:205]
	s_waitcnt lgkmcnt(1)
	v_pk_mul_f32 v[6:7], v[6:7], v[208:209]
	v_pk_mul_f32 v[16:17], v[16:17], v[202:203]
	v_pk_mul_f32 v[12:13], v[12:13], v[206:207]
	v_pk_mul_f32 v[8:9], v[8:9], v[210:211]
	s_waitcnt lgkmcnt(0)
	v_pk_mul_f32 v[4:5], v[4:5], v[224:225]
	v_pk_mul_f32 v[2:3], v[2:3], v[222:223]
	v_pk_mul_f32 v[62:63], v[62:63], v[200:201]
	v_pk_mul_f32 v[58:59], v[58:59], v[204:205]
	v_pk_mul_f32 v[54:55], v[54:55], v[208:209]
	v_pk_mul_f32 v[64:65], v[64:65], v[202:203]
	v_pk_mul_f32 v[60:61], v[60:61], v[206:207]
	v_pk_mul_f32 v[56:57], v[56:57], v[210:211]
	v_pk_mul_f32 v[52:53], v[52:53], v[224:225]
	v_pk_mul_f32 v[50:51], v[50:51], v[222:223]
	v_pk_mul_f32 v[46:47], v[46:47], v[200:201]
	v_pk_mul_f32 v[42:43], v[42:43], v[204:205]
	v_pk_mul_f32 v[38:39], v[38:39], v[208:209]
	v_pk_mul_f32 v[48:49], v[48:49], v[202:203]
	v_pk_mul_f32 v[44:45], v[44:45], v[206:207]
	v_pk_mul_f32 v[40:41], v[40:41], v[210:211]
	v_pk_mul_f32 v[36:37], v[36:37], v[224:225]
	v_pk_mul_f32 v[34:35], v[34:35], v[222:223]
	v_pk_mul_f32 v[30:31], v[30:31], v[200:201]
	v_pk_mul_f32 v[26:27], v[26:27], v[204:205]
	v_pk_mul_f32 v[22:23], v[22:23], v[208:209]
	v_pk_mul_f32 v[32:33], v[32:33], v[202:203]
	v_pk_mul_f32 v[28:29], v[28:29], v[206:207]
	v_pk_mul_f32 v[24:25], v[24:25], v[210:211]
	v_pk_mul_f32 v[20:21], v[20:21], v[224:225]
	v_pk_mul_f32 v[18:19], v[18:19], v[222:223]
.LBB0_756:
	s_cmp_ge_u32 s41, s40
	s_waitcnt lgkmcnt(0)
	s_barrier
	s_cbranch_scc1 .Lmla_loop_exit
	s_branch .LBB0_748
.Lmla_loop_exit:
	v_mul_f32_e32 v194, 0xbf800000, v226
	v_mov_b32_e32 v130, v247
	v_bfe_u32 v96, v163, 11, 1
	v_mul_u32_u24_e32 v96, 0x700, v96
	v_sub_u32_e32 v165, v165, v96
	v_mov_b32_e32 v166, v227
	v_mov_b32_e32 v97, v227
	s_nop 1
	v_permlane32_swap_b32_e32 v166, v97
	v_add_f32_e32 v166, v166, v97
	v_add_u32_e32 v172, 0xffffd000, v172
	v_add_u32_e32 v173, 0xffffd000, v173
	v_add_u32_e32 v174, 0xffffd000, v174
	v_add_u32_e32 v175, 0xffffd000, v175
	v_add_u32_e32 v176, 0xffffd000, v176
	v_add_u32_e32 v177, 0xffffd000, v177
	v_add_u32_e32 v178, 0xffffd000, v178
	v_add_u32_e32 v179, 0xffffd000, v179
	v_add_u32_e32 v180, 0xffffd000, v180
	v_add_u32_e32 v181, 0xffffd000, v181
	v_add_u32_e32 v182, 0xffffd000, v182
	v_add_u32_e32 v183, 0xffffd000, v183
	v_add_u32_e32 v196, 0xe000, v172
	v_add_u32_e32 v195, 0xe000, v173
	v_add_u32_e32 v193, 0xe000, v174
	v_add_u32_e32 v192, 0xe000, v175
	v_add_u32_e32 v191, 0xe000, v176
	v_add_u32_e32 v190, 0xe000, v177
	v_add_u32_e32 v189, 0xe000, v178
	v_add_u32_e32 v188, 0xe000, v179
	v_add_u32_e32 v187, 0xe000, v180
	v_add_u32_e32 v186, 0xe000, v181
	v_add_u32_e32 v185, 0xe000, v182
	v_add_u32_e32 v184, 0xe000, v183
; #define SBAR() __builtin_amdgcn_sched_barrier(0)
; template <int OFF> DI s16x4 tr_read(int vb) { s16x4 r; asm volatile("ds_read_b64_tr_b16 %0, %1 offset:%2" : "=&v"(r) : "v"(vb), "i"(OFF) : "memory"); return r; }
; template <int D0> DI void pv_one(f32x16& od, int vb, bf16x8 pa0, bf16x8 pa1, bf16x8 pa2, bf16x8 pa3) {
;   const s16x4 l0 = tr_read<v_rd_off(D0, 0, 0)>(vb), h0 = tr_read<v_rd_off(D0, 0, 1)>(vb), l1 = tr_read<v_rd_off(D0, 1, 0)>(vb), h1 = tr_read<v_rd_off(D0, 1, 1)>(vb);
;   const s16x4 l2 = tr_read<v_rd_off(D0, 2, 0)>(vb), h2 = tr_read<v_rd_off(D0, 2, 1)>(vb), l3 = tr_read<v_rd_off(D0, 3, 0)>(vb), h3 = tr_read<v_rd_off(D0, 3, 1)>(vb);
;   asm volatile("s_waitcnt lgkmcnt(0)" ::: "memory"); SBAR();
;     ...
;   od = __builtin_amdgcn_mfma_f32_32x32x16_bf16(pa0, PK(l0, h0), od, 0, 0, 0);
;   od = __builtin_amdgcn_mfma_f32_32x32x16_bf16(pa1, PK(l1, h1), od, 0, 0, 0);
;   od = __builtin_amdgcn_mfma_f32_32x32x16_bf16(pa2, PK(l2, h2), od, 0, 0, 0);
;   od = __builtin_amdgcn_mfma_f32_32x32x16_bf16(pa3, PK(l3, h3), od, 0, 0, 0);
;     ...
; }
; DI void pv_d0(f32x16* o, int vb, bf16x8 pa0, bf16x8 pa1, bf16x8 pa2, bf16x8 pa3) {
;   pv_one<0>(o[0], vb, pa0, pa1, pa2, pa3); pv_one<1>(o[1], vb, pa0, pa1, pa2, pa3); pv_one<2>(o[2], vb, pa0, pa1, pa2, pa3); pv_one<3>(o[3], vb, pa0, pa1, pa2, pa3);
; }
; template <int DQK, int SDEPTH, bool OUT_BF16, int QREG = DQK / 16, bool OUT_F16 = false> ...
;     ...
;   SBAR(); QKT(pB0, pB1, K_lds + SHM_K);
;   finishSM(pA0, pA1, alA, l_reg, pa0, pa1, pa2, pa3); SBAR();
;   pv_d0(o, vb0, pa0, pa1, pa2, pa3); partialSM(pB0, pB1, m_reg, mnB, alB, SCALE);
.LBB0_758:
	ds_read_b128 v[66:69], v196
	ds_read_b128 v[70:73], v196 offset:12288
	s_waitcnt lgkmcnt(1)
	v_mfma_f32_32x32x16_bf16 v[82:97], v[66:69], v[110:113], 0
	s_waitcnt lgkmcnt(0)
	v_mfma_f32_32x32x16_bf16 v[66:81], v[70:73], v[110:113], 0
	ds_read_b128 v[110:113], v195
	ds_read_b128 v[144:147], v195 offset:12288
	s_waitcnt lgkmcnt(1)
	v_mfma_f32_32x32x16_bf16 v[82:97], v[110:113], v[106:109], v[82:97]
	s_waitcnt lgkmcnt(0)
	v_mfma_f32_32x32x16_bf16 v[66:81], v[144:147], v[106:109], v[66:81]
	ds_read_b128 v[106:109], v193
	ds_read_b128 v[110:113], v193 offset:12288
	s_waitcnt lgkmcnt(1)
	v_mfma_f32_32x32x16_bf16 v[82:97], v[106:109], v[102:105], v[82:97]
	s_waitcnt lgkmcnt(0)
	v_mfma_f32_32x32x16_bf16 v[66:81], v[110:113], v[102:105], v[66:81]
	ds_read_b128 v[102:105], v192
	ds_read_b128 v[106:109], v192 offset:12288
	s_waitcnt lgkmcnt(1)
	v_mfma_f32_32x32x16_bf16 v[82:97], v[102:105], v[98:101], v[82:97]
	s_waitcnt lgkmcnt(0)
	v_mfma_f32_32x32x16_bf16 v[66:81], v[106:109], v[98:101], v[66:81]
	ds_read_b128 v[98:101], v191
	ds_read_b128 v[102:105], v191 offset:12288
	ds_read_b128 v[106:109], v162
	s_waitcnt lgkmcnt(0)
	v_mfma_f32_32x32x16_bf16 v[82:97], v[98:101], v[106:109], v[82:97]
	v_mfma_f32_32x32x16_bf16 v[66:81], v[102:105], v[106:109], v[66:81]
	ds_read_b128 v[98:101], v190
	ds_read_b128 v[102:105], v190 offset:12288
	ds_read_b128 v[106:109], v162 offset:1024
	s_waitcnt lgkmcnt(0)
	v_mfma_f32_32x32x16_bf16 v[82:97], v[98:101], v[106:109], v[82:97]
	v_mfma_f32_32x32x16_bf16 v[66:81], v[102:105], v[106:109], v[66:81]
	ds_read_b128 v[98:101], v189
	ds_read_b128 v[102:105], v189 offset:12288
	ds_read_b128 v[106:109], v162 offset:2048
	s_waitcnt lgkmcnt(0)
	v_mfma_f32_32x32x16_bf16 v[82:97], v[98:101], v[106:109], v[82:97]
	v_mfma_f32_32x32x16_bf16 v[66:81], v[102:105], v[106:109], v[66:81]
	ds_read_b128 v[98:101], v188
	ds_read_b128 v[102:105], v188 offset:12288
	ds_read_b128 v[106:109], v162 offset:3072
	s_waitcnt lgkmcnt(0)
	v_mfma_f32_32x32x16_bf16 v[82:97], v[98:101], v[106:109], v[82:97]
	v_mfma_f32_32x32x16_bf16 v[66:81], v[102:105], v[106:109], v[66:81]
	ds_read_b128 v[98:101], v187
	ds_read_b128 v[102:105], v187 offset:12288
	ds_read_b128 v[106:109], v162 offset:4096
	s_waitcnt lgkmcnt(0)
	v_mfma_f32_32x32x16_bf16 v[82:97], v[98:101], v[106:109], v[82:97]
	v_mfma_f32_32x32x16_bf16 v[66:81], v[102:105], v[106:109], v[66:81]
	ds_read_b128 v[98:101], v186
	ds_read_b128 v[102:105], v186 offset:12288
	ds_read_b128 v[106:109], v162 offset:5120
	s_waitcnt lgkmcnt(0)
	v_mfma_f32_32x32x16_bf16 v[82:97], v[98:101], v[106:109], v[82:97]
	v_mfma_f32_32x32x16_bf16 v[66:81], v[102:105], v[106:109], v[66:81]
	ds_read_b128 v[98:101], v185
	ds_read_b128 v[102:105], v185 offset:12288
	ds_read_b128 v[106:109], v162 offset:6144
	s_waitcnt lgkmcnt(0)
	v_mfma_f32_32x32x16_bf16 v[82:97], v[98:101], v[106:109], v[82:97]
	v_mfma_f32_32x32x16_bf16 v[66:81], v[102:105], v[106:109], v[66:81]
	ds_read_b128 v[98:101], v184
	ds_read_b128 v[102:105], v184 offset:12288
	ds_read_b128 v[106:109], v162 offset:7168
	s_waitcnt lgkmcnt(0)
	v_mfma_f32_32x32x16_bf16 v[82:97], v[98:101], v[106:109], v[82:97]
	v_mfma_f32_32x32x16_bf16 v[66:81], v[102:105], v[106:109], v[66:81]
	v_mov_b32_e32 v100, v134
	v_mov_b32_e32 v101, v135
	v_mov_b32_e32 v102, v136
	v_mov_b32_e32 v103, v137
	v_mov_b32_e32 v104, v138
	v_mov_b32_e32 v105, v139
	v_mov_b32_e32 v106, v140
	v_mov_b32_e32 v107, v141
	v_mov_b32_e32 v108, v214
	v_mov_b32_e32 v109, v215
	v_mov_b32_e32 v110, v216
	v_mov_b32_e32 v111, v217
	v_mov_b32_e32 v112, v218
	v_mov_b32_e32 v113, v219
	v_mov_b32_e32 v114, v220
	v_mov_b32_e32 v115, v221
	v_mov_b32_e32 v98, v252
	v_mov_b32_e32 v99, v252
	s_nop 1
	v_permlane32_swap_b32_e32 v98, v99
	ds_read_b64_tr_b16 v[116:117], v163 offset:0x0
	ds_read_b64_tr_b16 v[118:119], v163 offset:0x100
	ds_read_b64_tr_b16 v[120:121], v163 offset:0x1000
	ds_read_b64_tr_b16 v[122:123], v163 offset:0x1100
	ds_read_b64_tr_b16 v[124:125], v163 offset:0x2000
	ds_read_b64_tr_b16 v[126:127], v163 offset:0x2100
	ds_read_b64_tr_b16 v[132:133], v163 offset:0x3000
	ds_read_b64_tr_b16 v[134:135], v163 offset:0x3100
	s_waitcnt lgkmcnt(0)
	s_nop 0
	v_mfma_f32_32x32x16_bf16 v[2:17], v[100:103], v[116:119], v[2:17]
	ds_read_b64_tr_b16 v[116:117], v163 offset:0x200
	ds_read_b64_tr_b16 v[118:119], v163 offset:0x300
	v_mfma_f32_32x32x16_bf16 v[2:17], v[104:107], v[120:123], v[2:17]
	ds_read_b64_tr_b16 v[120:121], v163 offset:0x1200
	ds_read_b64_tr_b16 v[122:123], v163 offset:0x1300
	v_mfma_f32_32x32x16_bf16 v[2:17], v[108:111], v[124:127], v[2:17]
	ds_read_b64_tr_b16 v[124:125], v163 offset:0x2200
	ds_read_b64_tr_b16 v[126:127], v163 offset:0x2300
	v_mfma_f32_32x32x16_bf16 v[2:17], v[112:115], v[132:135], v[2:17]
	ds_read_b64_tr_b16 v[132:133], v163 offset:0x3200
	ds_read_b64_tr_b16 v[134:135], v163 offset:0x3300
	s_waitcnt lgkmcnt(0)
; #define SBAR() __builtin_amdgcn_sched_barrier(0)
; template <int OFF> DI s16x4 tr_read(int vb) { s16x4 r; asm volatile("ds_read_b64_tr_b16 %0, %1 offset:%2" : "=&v"(r) : "v"(vb), "i"(OFF) : "memory"); return r; }
; DI void partialSM(f32x16& p0, f32x16& p1, float& m_reg, float& mn, float& alpha, const float SCALE) {
;   const float C = SCALE * 1.4426950408889634f;
;   float pmax = p0[0];
; #pragma unroll
;   for (int r = 1; r < 16; ++r) pmax = fmaxf(pmax, p0[r]);
; #pragma unroll
;   for (int r = 0; r < 16; ++r) pmax = fmaxf(pmax, p1[r]);
;   { auto rr = __builtin_amdgcn_permlane32_swap(__float_as_uint(pmax), __float_as_uint(pmax), false, false);
;     pmax = fmaxf(__uint_as_float(rr[0]), __uint_as_float(rr[1])); }
;   if (__builtin_expect(__all(pmax - m_reg <= THR / SCALE), 1)) { mn = m_reg; alpha = 1.f; }
;   else { mn = fmaxf(m_reg, pmax); alpha = __builtin_amdgcn_exp2f((m_reg - mn) * C); m_reg = mn; }
; template <int D0> DI void pv_one(f32x16& od, int vb, bf16x8 pa0, bf16x8 pa1, bf16x8 pa2, bf16x8 pa3) {
;   const s16x4 l0 = tr_read<v_rd_off(D0, 0, 0)>(vb), h0 = tr_read<v_rd_off(D0, 0, 1)>(vb), l1 = tr_read<v_rd_off(D0, 1, 0)>(vb), h1 = tr_read<v_rd_off(D0, 1, 1)>(vb);
;   const s16x4 l2 = tr_read<v_rd_off(D0, 2, 0)>(vb), h2 = tr_read<v_rd_off(D0, 2, 1)>(vb), l3 = tr_read<v_rd_off(D0, 3, 0)>(vb), h3 = tr_read<v_rd_off(D0, 3, 1)>(vb);
;   asm volatile("s_waitcnt lgkmcnt(0)" ::: "memory"); SBAR();
;     ...
;   od = __builtin_amdgcn_mfma_f32_32x32x16_bf16(pa0, PK(l0, h0), od, 0, 0, 0);
;   od = __builtin_amdgcn_mfma_f32_32x32x16_bf16(pa1, PK(l1, h1), od, 0, 0, 0);
;   od = __builtin_amdgcn_mfma_f32_32x32x16_bf16(pa2, PK(l2, h2), od, 0, 0, 0);
;   od = __builtin_amdgcn_mfma_f32_32x32x16_bf16(pa3, PK(l3, h3), od, 0, 0, 0);
;     ...
; }
; DI void pv_d0(f32x16* o, int vb, bf16x8 pa0, bf16x8 pa1, bf16x8 pa2, bf16x8 pa3) {
;   pv_one<0>(o[0], vb, pa0, pa1, pa2, pa3); pv_one<1>(o[1], vb, pa0, pa1, pa2, pa3); pv_one<2>(o[2], vb, pa0, pa1, pa2, pa3); pv_one<3>(o[3], vb, pa0, pa1, pa2, pa3);
; }
	v_mfma_f32_32x32x16_bf16 v[50:65], v[100:103], v[116:119], v[50:65]
	ds_read_b64_tr_b16 v[116:117], v163 offset:0x400
	ds_read_b64_tr_b16 v[118:119], v163 offset:0x500
	v_mfma_f32_32x32x16_bf16 v[50:65], v[104:107], v[120:123], v[50:65]
	ds_read_b64_tr_b16 v[120:121], v163 offset:0x1400
	ds_read_b64_tr_b16 v[122:123], v163 offset:0x1500
	v_mfma_f32_32x32x16_bf16 v[50:65], v[108:111], v[124:127], v[50:65]
	ds_read_b64_tr_b16 v[124:125], v163 offset:0x2400
	ds_read_b64_tr_b16 v[126:127], v163 offset:0x2500
	v_mfma_f32_32x32x16_bf16 v[50:65], v[112:115], v[132:135], v[50:65]
	ds_read_b64_tr_b16 v[132:133], v163 offset:0x3400
	ds_read_b64_tr_b16 v[134:135], v163 offset:0x3500
	s_waitcnt lgkmcnt(0)
	v_mfma_f32_32x32x16_bf16 v[34:49], v[100:103], v[116:119], v[34:49]
	ds_read_b64_tr_b16 v[116:117], v163 offset:0x600
	ds_read_b64_tr_b16 v[118:119], v163 offset:0x700
	v_mfma_f32_32x32x16_bf16 v[34:49], v[104:107], v[120:123], v[34:49]
	ds_read_b64_tr_b16 v[120:121], v163 offset:0x1600
	ds_read_b64_tr_b16 v[122:123], v163 offset:0x1700
	v_mfma_f32_32x32x16_bf16 v[34:49], v[108:111], v[124:127], v[34:49]
	ds_read_b64_tr_b16 v[124:125], v163 offset:0x2600
	ds_read_b64_tr_b16 v[126:127], v163 offset:0x2700
	v_mfma_f32_32x32x16_bf16 v[34:49], v[112:115], v[132:135], v[34:49]
	ds_read_b64_tr_b16 v[132:133], v163 offset:0x3600
	ds_read_b64_tr_b16 v[134:135], v163 offset:0x3700
	s_waitcnt lgkmcnt(0)
	v_mfma_f32_32x32x16_bf16 v[18:33], v[100:103], v[116:119], v[18:33]
	v_max_f32_e32 v100, v83, v83
	v_max_f32_e32 v101, v82, v82
	v_max_f32_e32 v100, v101, v100
	v_max3_f32 v100, v100, v84, v85
	v_max3_f32 v100, v100, v86, v87
	v_max3_f32 v100, v100, v88, v89
	v_max3_f32 v100, v100, v90, v91
	v_max3_f32 v100, v100, v92, v93
	v_max3_f32 v100, v100, v94, v95
	v_mfma_f32_32x32x16_bf16 v[18:33], v[104:107], v[120:123], v[18:33]
	v_max3_f32 v100, v100, v96, v97
	v_max3_f32 v100, v100, v66, v67
	v_max3_f32 v100, v100, v68, v69
	v_max3_f32 v100, v100, v70, v71
	v_max3_f32 v100, v100, v72, v73
	v_max3_f32 v100, v100, v74, v75
	v_max3_f32 v100, v100, v76, v77
	v_max3_f32 v100, v100, v78, v79
	v_mfma_f32_32x32x16_bf16 v[18:33], v[108:111], v[124:127], v[18:33]
	v_max3_f32 v100, v100, v80, v81
	v_mov_b32_e32 v101, v100
	s_nop 1
	v_permlane32_swap_b32_e32 v100, v101
	v_max_f32_e32 v101, v101, v101
	v_max_f32_e32 v100, v100, v100
	v_max_f32_e32 v100, v100, v101
	v_sub_f32_e32 v101, v100, v194
	v_cmp_ge_f32_e32 vcc, 0x4138aa3b, v101
	v_max_f32_e32 v101, v194, v194
	v_max_f32_e32 v101, v101, v100
	v_mfma_f32_32x32x16_bf16 v[18:33], v[112:115], v[132:135], v[18:33]
	v_sub_f32_e32 v100, v194, v101
	v_mul_f32_e32 v100, 0x3f800000, v100
	v_exp_f32_e32 v100, v100
	s_cmp_eq_u64 vcc, exec
	s_cselect_b64 s[2:3], -1, 0
	v_cndmask_b32_e64 v100, v100, 1.0, s[2:3]
	v_cmp_gt_f32_e32 vcc, 1.0, v100
	s_barrier
	s_cbranch_vccz .LBB0_762
	s_and_saveexec_b64 s[10:11], s[0:1]
	ds_write_b32 v164, v100 offset:128
	s_or_b64 exec, exec, s[10:11]
	s_waitcnt lgkmcnt(0)
	v_add_u32_e32 v114, v143, v0
	ds_read_b128 v[102:105], v114 offset:224
	ds_read_b128 v[106:109], v114 offset:192
	ds_read_b128 v[110:113], v114 offset:160
	ds_read_b128 v[114:117], v114 offset:128
	s_waitcnt lgkmcnt(3)
	v_pk_mul_f32 v[14:15], v[14:15], v[102:103]
	s_waitcnt lgkmcnt(2)
	v_pk_mul_f32 v[10:11], v[10:11], v[106:107]
	s_waitcnt lgkmcnt(1)
	v_pk_mul_f32 v[6:7], v[6:7], v[110:111]
	v_pk_mul_f32 v[16:17], v[16:17], v[104:105]
	v_pk_mul_f32 v[12:13], v[12:13], v[108:109]
	v_pk_mul_f32 v[8:9], v[8:9], v[112:113]
	s_waitcnt lgkmcnt(0)
	v_pk_mul_f32 v[4:5], v[4:5], v[116:117]
	v_pk_mul_f32 v[2:3], v[2:3], v[114:115]
	v_pk_mul_f32 v[62:63], v[62:63], v[102:103]
	v_pk_mul_f32 v[58:59], v[58:59], v[106:107]
	v_pk_mul_f32 v[54:55], v[54:55], v[110:111]
	v_pk_mul_f32 v[64:65], v[64:65], v[104:105]
	v_pk_mul_f32 v[60:61], v[60:61], v[108:109]
	v_pk_mul_f32 v[56:57], v[56:57], v[112:113]
	v_pk_mul_f32 v[52:53], v[52:53], v[116:117]
	v_pk_mul_f32 v[50:51], v[50:51], v[114:115]
	v_pk_mul_f32 v[46:47], v[46:47], v[102:103]
	v_pk_mul_f32 v[42:43], v[42:43], v[106:107]
	v_pk_mul_f32 v[38:39], v[38:39], v[110:111]
	v_pk_mul_f32 v[48:49], v[48:49], v[104:105]
	v_pk_mul_f32 v[44:45], v[44:45], v[108:109]
	v_pk_mul_f32 v[40:41], v[40:41], v[112:113]
	v_pk_mul_f32 v[36:37], v[36:37], v[116:117]
	v_pk_mul_f32 v[34:35], v[34:35], v[114:115]
	v_pk_mul_f32 v[30:31], v[30:31], v[102:103]
	v_pk_mul_f32 v[26:27], v[26:27], v[106:107]
	v_pk_mul_f32 v[22:23], v[22:23], v[110:111]
	v_pk_mul_f32 v[32:33], v[32:33], v[104:105]
	v_pk_mul_f32 v[28:29], v[28:29], v[108:109]
	v_pk_mul_f32 v[24:25], v[24:25], v[112:113]
	v_pk_mul_f32 v[20:21], v[20:21], v[116:117]
	v_pk_mul_f32 v[18:19], v[18:19], v[114:115]
